# k-loop priority 2 for the younger and 1 for the older co-resident workgroup (0 outside the k-loops)
# baseline (speedup 1.0000x reference)
; template <class Epi>
; DEV void gemm_tile(const bf16_t* __restrict__ A, int lda, const bf16_t* __restrict__ Bt, int ldb, int K, int tm, int tn, char* smem, const Epi& epi) {
;     ...
;     const int lrow = tid >> 3, lcc = (tid & 7) * 8, lsw = (((tid & 7) ^ (lrow & 7)) * 8);
;     const bf16_t* Ag = A + (size_t)(tm * 128 + lrow) * lda + lcc;
;     const bf16_t* Bg = Bt + (size_t)(tn * 128 + lrow) * ldb + lcc;
;     f32x4 acc[4][4];
; #pragma unroll
;     for (int m = 0; m < 4; ++m)
; #pragma unroll
;         for (int n = 0; n < 4; ++n) acc[m][n] = (f32x4){0.f, 0.f, 0.f, 0.f};
;     const int gsw = (((tid & 7) ^ (lrow & 7)) * 8);
;     const bf16_t* Ad = A + (size_t)(tm * 128 + lrow) * lda + gsw;
;     const bf16_t* Bd = Bt + (size_t)(tn * 128 + lrow) * ldb + gsw;
;     char* Asb = (char*)As; char* Bsb = (char*)Bs;
;     ...
;     const int nk = K >> 6;
;     G_DMA(0, 0);
;     asm volatile("s_waitcnt vmcnt(0)" ::: "memory");
;     __syncthreads();
; template <class Epi>
; DEV void gemm_phase(const bf16_t* A, int lda, const bf16_t* Bt, int ldb, int K, int ntm, int ntn, bool skip_ctx, char* smem, const Epi& epi) {
;     ...
;         for (int q = slot; q < per; q += nper) {
;             int tm, tn;
;             if (q < fullq) { const int tb = q / (R * 8), r = q - tb * (R * 8); tm = r >> 3; tn = tb * 8 + (r & 7); }
;             else { const int q2 = q - fullq; tm = q2 / w; tn = nfb * 8 + (q2 - tm * w); }
;             tm += xcd * R;
;             if (skip_ctx && ((tm * 128) % TT) >= SEQ) continue;
;             gemm_tile(A, lda, Bt, ldb, K, tm, tn, smem, epi);
.LBB0_97:
	v_readlane_b32 s2, v253, 31
	s_add_i32 s62, s42, s2
	s_lshl_b32 s2, s62, 7
	s_mul_hi_i32 s3, s2, 0x38e38e39
	s_lshr_b32 s38, s3, 31
	s_ashr_i32 s3, s3, 9
	s_add_i32 s3, s3, s38
	s_mulk_i32 s3, 0x900
	s_sub_i32 s92, s2, s3
	s_cmpk_gt_i32 s92, 0x7ff
	s_cselect_b64 s[38:39], -1, 0
	s_and_b64 s[38:39], s[54:55], s[38:39]
	s_and_b64 vcc, exec, s[38:39]
	s_cbranch_vccnz .LBB0_92
	v_mov_b32_e32 v12, v163
	s_mov_b64 s[38:39], 0x10000
	v_ashrrev_i32_e32 v14, 3, v12
	v_add_u32_e32 v2, s2, v14
	v_lshl_add_u32 v4, s43, 7, v14
	v_ashrrev_i32_e32 v3, 31, v2
	v_ashrrev_i32_e32 v5, 31, v4
	s_waitcnt vmcnt(10)
	v_xor_b32_e32 v0, v14, v12
	v_lshlrev_b64 v[2:3], 11, v[2:3]
	v_lshlrev_b64 v[4:5], 11, v[4:5]
	v_lshlrev_b32_e32 v0, 4, v0
	v_lshl_add_u64 v[6:7], s[26:27], 0, v[2:3]
	v_lshl_add_u64 v[8:9], s[48:49], 0, v[4:5]
	v_and_b32_e32 v0, 0x70, v0
	v_lshl_add_u64 v[6:7], v[6:7], 0, v[0:1]
	v_lshl_add_u64 v[8:9], v[8:9], 0, v[0:1]
	v_lshlrev_b32_e32 v0, 4, v12
	v_add_u32_e32 v0, 16, v0
	v_add_u32_e32 v76, 0x8000, v0
	v_readfirstlane_b32 s2, v0
	s_mov_b32 m0, s2
	v_readfirstlane_b32 s2, v76
	v_add_u32_e32 v77, 0x1000, v0
	global_load_lds_dwordx4 v[6:7], off
	s_mov_b32 m0, s2
	v_readfirstlane_b32 s2, v77
	v_add_u32_e32 v78, 0x9000, v0
	global_load_lds_dwordx4 v[8:9], off
	v_lshl_add_u64 v[10:11], v[6:7], 0, s[38:39]
	s_mov_b32 m0, s2
	v_readfirstlane_b32 s2, v78
	v_add_u32_e32 v79, 0x2000, v0
	global_load_lds_dwordx4 v[10:11], off
	v_lshl_add_u64 v[10:11], v[8:9], 0, s[38:39]
	s_mov_b32 m0, s2
	s_mov_b64 s[38:39], 0x20000
	v_readfirstlane_b32 s2, v79
	v_add_u32_e32 v80, 0xa000, v0
	global_load_lds_dwordx4 v[10:11], off
	v_lshl_add_u64 v[10:11], v[6:7], 0, s[38:39]
	s_mov_b32 m0, s2
	v_readfirstlane_b32 s2, v80
	v_add_u32_e32 v81, 0x3000, v0
	global_load_lds_dwordx4 v[10:11], off
	v_lshl_add_u64 v[10:11], v[8:9], 0, s[38:39]
	s_mov_b32 m0, s2
	s_mov_b64 s[38:39], 0x30000
	v_readfirstlane_b32 s2, v81
	v_add_u32_e32 v82, 0xb000, v0
	global_load_lds_dwordx4 v[10:11], off
	v_lshl_add_u64 v[6:7], v[6:7], 0, s[38:39]
	s_mov_b32 m0, s2
	v_readfirstlane_b32 s2, v82
	global_load_lds_dwordx4 v[6:7], off
	v_lshl_add_u64 v[6:7], v[8:9], 0, s[38:39]
	s_mov_b32 m0, s2
	v_lshrrev_b32_e32 v13, 4, v12
	global_load_lds_dwordx4 v[6:7], off
	v_and_b32_e32 v75, 15, v12
	v_ashrrev_i32_e32 v84, 7, v12
	v_bfe_u32 v83, v12, 4, 2
	v_and_b32_e32 v8, 7, v12
	v_lshlrev_b32_e32 v6, 13, v84
	v_lshlrev_b32_e32 v7, 7, v75
	v_bitop3_b32 v9, v13, v8, 3 bitop3:0x6c
	v_bitop3_b32 v8, v83, v8, 4 bitop3:0x36
	v_add3_u32 v6, 16, v6, v7
	v_lshlrev_b32_e32 v9, 4, v9
	v_lshlrev_b32_e32 v8, 4, v8
	v_add_u32_e32 v85, v6, v9
	v_add_u32_e32 v87, v6, v8
	v_bitop3_b32 v6, v14, 7, v12 bitop3:0x48
	v_bfe_u32 v74, v12, 6, 1
	v_lshlrev_b32_e32 v6, 4, v6
	s_waitcnt vmcnt(0)
	v_lshlrev_b32_e32 v10, 13, v74
	v_or_b32_e32 v2, v2, v6
	v_add3_u32 v7, 16, v10, v7
	v_or_b32_e32 v4, v4, v6
	v_lshl_add_u64 v[68:69], s[60:61], 0, v[2:3]
	v_mov_b32_e32 v2, 0
	v_add_u32_e32 v86, v7, v9
	v_add_u32_e32 v88, v7, v8
	v_lshl_add_u64 v[66:67], s[46:47], 0, v[4:5]
	s_mov_b64 s[2:3], 0
	v_mov_b32_e32 v3, v2
	v_mov_b32_e32 v4, v2
	v_mov_b32_e32 v5, v2
	v_mov_b32_e32 v6, v2
	v_mov_b32_e32 v7, v2
	v_mov_b32_e32 v8, v2
	v_mov_b32_e32 v9, v2
	v_mov_b32_e32 v10, v2
	v_mov_b32_e32 v11, v2
	v_mov_b32_e32 v12, v2
	v_mov_b32_e32 v13, v2
	v_mov_b32_e32 v14, v2
	v_mov_b32_e32 v15, v2
	v_mov_b32_e32 v16, v2
	v_mov_b32_e32 v17, v2
	s_waitcnt vmcnt(0)
	v_mov_b32_e32 v18, v2
	v_mov_b32_e32 v19, v2
	v_mov_b32_e32 v20, v2
	v_mov_b32_e32 v21, v2
	v_mov_b32_e32 v22, v2
	v_mov_b32_e32 v23, v2
	v_mov_b32_e32 v24, v2
	v_mov_b32_e32 v25, v2
	v_mov_b32_e32 v26, v2
	v_mov_b32_e32 v27, v2
	v_mov_b32_e32 v28, v2
	v_mov_b32_e32 v29, v2
	v_mov_b32_e32 v30, v2
	v_mov_b32_e32 v31, v2
	v_mov_b32_e32 v32, v2
	v_mov_b32_e32 v33, v2
	v_mov_b32_e32 v34, v2
	v_mov_b32_e32 v35, v2
	v_mov_b32_e32 v36, v2
	v_mov_b32_e32 v37, v2
	v_mov_b32_e32 v38, v2
	v_mov_b32_e32 v39, v2
	v_mov_b32_e32 v40, v2
	v_mov_b32_e32 v41, v2
	v_mov_b32_e32 v42, v2
	v_mov_b32_e32 v43, v2
	v_mov_b32_e32 v44, v2
	v_mov_b32_e32 v45, v2
	v_mov_b32_e32 v46, v2
	v_mov_b32_e32 v47, v2
	v_mov_b32_e32 v48, v2
	v_mov_b32_e32 v49, v2
	v_mov_b32_e32 v50, v2
	v_mov_b32_e32 v51, v2
	v_mov_b32_e32 v52, v2
	v_mov_b32_e32 v53, v2
	v_mov_b32_e32 v54, v2
	v_mov_b32_e32 v55, v2
	v_mov_b32_e32 v56, v2
	v_mov_b32_e32 v57, v2
	v_mov_b32_e32 v58, v2
	v_mov_b32_e32 v59, v2
	v_mov_b32_e32 v60, v2
	v_mov_b32_e32 v61, v2
	v_mov_b32_e32 v62, v2
	v_mov_b32_e32 v63, v2
	v_mov_b32_e32 v64, v2
	v_mov_b32_e32 v65, v2
	s_waitcnt vmcnt(0) lgkmcnt(0)
	s_barrier
; template <class Epi>
; DEV void gemm_tile(const bf16_t* __restrict__ A, int lda, const bf16_t* __restrict__ Bt, int ldb, int K, int tm, int tn, char* smem, const Epi& epi) {
;     ...
;     const int lrow = tid >> 3, lcc = (tid & 7) * 8, lsw = (((tid & 7) ^ (lrow & 7)) * 8);
;     const bf16_t* Ag = A + (size_t)(tm * 128 + lrow) * lda + lcc;
;     const bf16_t* Bg = Bt + (size_t)(tn * 128 + lrow) * ldb + lcc;
;     f32x4 acc[4][4];
; #pragma unroll
;     for (int m = 0; m < 4; ++m)
; #pragma unroll
;         for (int n = 0; n < 4; ++n) acc[m][n] = (f32x4){0.f, 0.f, 0.f, 0.f};
;     const int gsw = (((tid & 7) ^ (lrow & 7)) * 8);
;     const bf16_t* Ad = A + (size_t)(tm * 128 + lrow) * lda + gsw;
;     const bf16_t* Bd = Bt + (size_t)(tn * 128 + lrow) * ldb + gsw;
;     char* Asb = (char*)As; char* Bsb = (char*)Bs;
;     ...
;     const int nk = K >> 6;
;     G_DMA(0, 0);
;     asm volatile("s_waitcnt vmcnt(0)" ::: "memory");
;     __syncthreads();
	v_writelane_b32 v255, s88, 24
	v_writelane_b32 v255, s89, 25
	v_writelane_b32 v255, s90, 26
	v_writelane_b32 v255, s91, 27
	v_writelane_b32 v255, s92, 28
	v_writelane_b32 v255, s93, 29
	v_writelane_b32 v255, s94, 30
	v_writelane_b32 v255, s95, 31
	v_readfirstlane_b32 s88, v68
	v_readfirstlane_b32 s89, v69
	v_readfirstlane_b32 s90, v66
	v_readfirstlane_b32 s91, v67
	v_lshl_add_u32 v242, v163, 4, 16
	s_and_b32 s88, s88, 0xffffff80
	s_and_b32 s90, s90, 0xffffff80
	v_readfirstlane_b32 s93, v242
	v_subrev_u32_e32 v250, s88, v68
	v_subrev_u32_e32 v246, s90, v66
	v_add_u32_e32 v249, 0x10000, v250
	v_add_u32_e32 v245, 0x10000, v246
	v_add_u32_e32 v248, 0x20000, v250
	v_add_u32_e32 v244, 0x20000, v246
	v_add_u32_e32 v247, 0x30000, v250
	v_add_u32_e32 v243, 0x30000, v246
	s_add_u32 s94, s93, 0x4000
	s_add_u32 s88, s88, 0x8688080
	s_addc_u32 s89, s89, 0
	s_add_u32 s90, s90, 0x2b68080
	s_addc_u32 s91, s91, 0
	v_and_b32_e32 v242, 15, v163
	v_lshlrev_b32_e32 v242, 7, v242
	v_bfe_u32 v153, v163, 4, 2
	v_and_b32_e32 v154, 7, v163
	v_xor_b32_e32 v153, v153, v154
	v_lshlrev_b32_e32 v154, 4, v153
	v_xor_b32_e32 v153, 4, v153
	v_lshlrev_b32_e32 v153, 4, v153
	v_lshrrev_b32_e32 v89, 7, v163
	v_lshl_add_u32 v89, v89, 13, v242
	v_add_u32_e32 v89, 16, v89
	v_bfe_u32 v151, v163, 6, 1
	v_lshl_add_u32 v151, v151, 13, v242
	v_add_u32_e32 v151, 16, v151
	v_add_u32_e32 v150, v89, v153
	v_add_u32_e32 v152, v151, v153
	v_add_u32_e32 v89, v89, v154
	v_add_u32_e32 v151, v151, v154
	s_mov_b32 m0, s94
	s_nop 0
	global_load_lds_dwordx4 v250, s[88:89]
	s_add_u32 m0, m0, 0x1000
	s_nop 0
	global_load_lds_dwordx4 v249, s[88:89]
	s_add_u32 m0, m0, 0x1000
	s_nop 0
	global_load_lds_dwordx4 v248, s[88:89]
	s_add_u32 m0, m0, 0x1000
	s_nop 0
	global_load_lds_dwordx4 v247, s[88:89]
	s_add_u32 m0, m0, 0x5000
	s_nop 0
	global_load_lds_dwordx4 v246, s[90:91]
	s_add_u32 m0, m0, 0x1000
	s_nop 0
	global_load_lds_dwordx4 v245, s[90:91]
	s_add_u32 m0, m0, 0x1000
	s_nop 0
	global_load_lds_dwordx4 v244, s[90:91]
	s_add_u32 m0, m0, 0x1000
	s_nop 0
	global_load_lds_dwordx4 v243, s[90:91]
	s_add_u32 s88, s88, 0x80
	s_addc_u32 s89, s89, 0
	s_add_u32 s90, s90, 0x80
	s_addc_u32 s91, s91, 0
	ds_read_b128 v[70:73], v89
	ds_read_b128 v[90:93], v89 offset:2048
	ds_read_b128 v[94:97], v89 offset:4096
	ds_read_b128 v[98:101], v89 offset:6144
	ds_read_b128 v[102:105], v151 offset:32768
	ds_read_b128 v[106:109], v151 offset:34816
	ds_read_b128 v[110:113], v151 offset:36864
	ds_read_b128 v[114:117], v151 offset:38912
	v_readlane_b32 s95, v251, 0
	s_nop 0
	s_cmp_lt_u32 s95, 0x100
	s_setprio 1
	s_cbranch_scc1 .Lgemm_up_lowprio
	s_setprio 2

; #define G_MMA(ks_) __builtin_amdgcn_s_setprio(1); _Pragma("unroll") for (int m = 0; m < 4; ++m) \
;         _Pragma("unroll") for (int n = 0; n < 4; ++n) acc[m][n] = __builtin_amdgcn_mfma_f32_16x16x32_bf16(bfv##ks_[n], af##ks_[m], acc[m][n], 0, 0, 0); __builtin_amdgcn_s_setprio(0);
; template <class Epi>
; DEV void gemm_tile(const bf16_t* __restrict__ A, int lda, const bf16_t* __restrict__ Bt, int ldb, int K, int tm, int tn, char* smem, const Epi& epi) {
;     ...
;     const int nk = K >> 6;
;     G_DMA(0, 0);
;     asm volatile("s_waitcnt vmcnt(0)" ::: "memory");
;     __syncthreads();
; #pragma unroll 4
;     for (int kt = 0; kt < nk; ++kt) {
;         const int cur = kt & 1;
;         if (kt + 1 < nk) G_DMA(cur ^ 1, kt + 1);
;         {
;             G_FRAGS(cur, 0)
;             G_MMA(0)
;             G_FRAGS(cur, 1)
;             G_MMA(1)
;         }
;         asm volatile("s_waitcnt vmcnt(0)" ::: "memory");
;         __syncthreads();
;     }
.Lgemm_up_loop:
	ds_read_b128 v[118:121], v150
	ds_read_b128 v[122:125], v150 offset:2048
	ds_read_b128 v[126:129], v150 offset:4096
	ds_read_b128 v[130:133], v150 offset:6144
	ds_read_b128 v[134:137], v152 offset:32768
	ds_read_b128 v[138:141], v152 offset:34816
	ds_read_b128 v[142:145], v152 offset:36864
	ds_read_b128 v[146:149], v152 offset:38912
	s_waitcnt lgkmcnt(8)
	v_mfma_f32_16x16x32_bf16 v[2:5], v[102:105], v[70:73], v[2:5]
	v_mfma_f32_16x16x32_bf16 v[6:9], v[106:109], v[70:73], v[6:9]
	v_mfma_f32_16x16x32_bf16 v[10:13], v[110:113], v[70:73], v[10:13]
	v_mfma_f32_16x16x32_bf16 v[14:17], v[114:117], v[70:73], v[14:17]
	v_mfma_f32_16x16x32_bf16 v[18:21], v[102:105], v[90:93], v[18:21]
	v_mfma_f32_16x16x32_bf16 v[22:25], v[106:109], v[90:93], v[22:25]
	v_mfma_f32_16x16x32_bf16 v[26:29], v[110:113], v[90:93], v[26:29]
	v_mfma_f32_16x16x32_bf16 v[30:33], v[114:117], v[90:93], v[30:33]
	v_mfma_f32_16x16x32_bf16 v[34:37], v[102:105], v[94:97], v[34:37]
	v_mfma_f32_16x16x32_bf16 v[38:41], v[106:109], v[94:97], v[38:41]
	v_mfma_f32_16x16x32_bf16 v[42:45], v[110:113], v[94:97], v[42:45]
	v_mfma_f32_16x16x32_bf16 v[46:49], v[114:117], v[94:97], v[46:49]
	v_mfma_f32_16x16x32_bf16 v[50:53], v[102:105], v[98:101], v[50:53]
	v_mfma_f32_16x16x32_bf16 v[54:57], v[106:109], v[98:101], v[54:57]
	v_mfma_f32_16x16x32_bf16 v[58:61], v[110:113], v[98:101], v[58:61]
	v_mfma_f32_16x16x32_bf16 v[62:65], v[114:117], v[98:101], v[62:65]
	s_waitcnt vmcnt(0) lgkmcnt(0)
	s_barrier
	ds_read_b128 v[70:73], v89 offset:16384
	ds_read_b128 v[90:93], v89 offset:18432
	ds_read_b128 v[94:97], v89 offset:20480
	ds_read_b128 v[98:101], v89 offset:22528
	ds_read_b128 v[102:105], v151 offset:49152
	ds_read_b128 v[106:109], v151 offset:51200
	ds_read_b128 v[110:113], v151 offset:53248
	ds_read_b128 v[114:117], v151 offset:55296
	s_mov_b32 m0, s93
	v_mfma_f32_16x16x32_bf16 v[2:5], v[134:137], v[118:121], v[2:5]
	global_load_lds_dwordx4 v250, s[88:89]
	s_add_u32 m0, m0, 0x1000
	v_mfma_f32_16x16x32_bf16 v[6:9], v[138:141], v[118:121], v[6:9]
	global_load_lds_dwordx4 v249, s[88:89]
	s_add_u32 m0, m0, 0x1000
	v_mfma_f32_16x16x32_bf16 v[10:13], v[142:145], v[118:121], v[10:13]
	global_load_lds_dwordx4 v248, s[88:89]
	s_add_u32 m0, m0, 0x1000
	v_mfma_f32_16x16x32_bf16 v[14:17], v[146:149], v[118:121], v[14:17]
	global_load_lds_dwordx4 v247, s[88:89]
	s_add_u32 m0, m0, 0x5000
	v_mfma_f32_16x16x32_bf16 v[18:21], v[134:137], v[122:125], v[18:21]
	global_load_lds_dwordx4 v246, s[90:91]
	s_add_u32 m0, m0, 0x1000
	v_mfma_f32_16x16x32_bf16 v[22:25], v[138:141], v[122:125], v[22:25]
	global_load_lds_dwordx4 v245, s[90:91]
	s_add_u32 m0, m0, 0x1000
	v_mfma_f32_16x16x32_bf16 v[26:29], v[142:145], v[122:125], v[26:29]
	global_load_lds_dwordx4 v244, s[90:91]
	s_add_u32 m0, m0, 0x1000
	v_mfma_f32_16x16x32_bf16 v[30:33], v[146:149], v[122:125], v[30:33]
	global_load_lds_dwordx4 v243, s[90:91]
	v_mfma_f32_16x16x32_bf16 v[34:37], v[134:137], v[126:129], v[34:37]
	s_add_u32 s88, s88, 0x80
	v_mfma_f32_16x16x32_bf16 v[38:41], v[138:141], v[126:129], v[38:41]
	s_addc_u32 s89, s89, 0
	v_mfma_f32_16x16x32_bf16 v[42:45], v[142:145], v[126:129], v[42:45]
	s_add_u32 s90, s90, 0x80
	v_mfma_f32_16x16x32_bf16 v[46:49], v[146:149], v[126:129], v[46:49]
	s_addc_u32 s91, s91, 0
	v_mfma_f32_16x16x32_bf16 v[50:53], v[134:137], v[130:133], v[50:53]
	v_mfma_f32_16x16x32_bf16 v[54:57], v[138:141], v[130:133], v[54:57]
	v_mfma_f32_16x16x32_bf16 v[58:61], v[142:145], v[130:133], v[58:61]
	v_mfma_f32_16x16x32_bf16 v[62:65], v[146:149], v[130:133], v[62:65]
	ds_read_b128 v[118:121], v150 offset:16384
	ds_read_b128 v[122:125], v150 offset:18432
	ds_read_b128 v[126:129], v150 offset:20480
	ds_read_b128 v[130:133], v150 offset:22528
	ds_read_b128 v[134:137], v152 offset:49152
	ds_read_b128 v[138:141], v152 offset:51200
	ds_read_b128 v[142:145], v152 offset:53248
	ds_read_b128 v[146:149], v152 offset:55296
	s_waitcnt lgkmcnt(8)
	v_mfma_f32_16x16x32_bf16 v[2:5], v[102:105], v[70:73], v[2:5]
	v_mfma_f32_16x16x32_bf16 v[6:9], v[106:109], v[70:73], v[6:9]
	v_mfma_f32_16x16x32_bf16 v[10:13], v[110:113], v[70:73], v[10:13]
	v_mfma_f32_16x16x32_bf16 v[14:17], v[114:117], v[70:73], v[14:17]
	v_mfma_f32_16x16x32_bf16 v[18:21], v[102:105], v[90:93], v[18:21]
	v_mfma_f32_16x16x32_bf16 v[22:25], v[106:109], v[90:93], v[22:25]
	v_mfma_f32_16x16x32_bf16 v[26:29], v[110:113], v[90:93], v[26:29]
	v_mfma_f32_16x16x32_bf16 v[30:33], v[114:117], v[90:93], v[30:33]
	v_mfma_f32_16x16x32_bf16 v[34:37], v[102:105], v[94:97], v[34:37]
	v_mfma_f32_16x16x32_bf16 v[38:41], v[106:109], v[94:97], v[38:41]
	v_mfma_f32_16x16x32_bf16 v[42:45], v[110:113], v[94:97], v[42:45]
	v_mfma_f32_16x16x32_bf16 v[46:49], v[114:117], v[94:97], v[46:49]
	v_mfma_f32_16x16x32_bf16 v[50:53], v[102:105], v[98:101], v[50:53]
	v_mfma_f32_16x16x32_bf16 v[54:57], v[106:109], v[98:101], v[54:57]
	v_mfma_f32_16x16x32_bf16 v[58:61], v[110:113], v[98:101], v[58:61]
	v_mfma_f32_16x16x32_bf16 v[62:65], v[114:117], v[98:101], v[62:65]
	s_waitcnt vmcnt(0) lgkmcnt(0)
	s_barrier
; #define G_MMA(ks_) __builtin_amdgcn_s_setprio(1); _Pragma("unroll") for (int m = 0; m < 4; ++m) \
;         _Pragma("unroll") for (int n = 0; n < 4; ++n) acc[m][n] = __builtin_amdgcn_mfma_f32_16x16x32_bf16(bfv##ks_[n], af##ks_[m], acc[m][n], 0, 0, 0); __builtin_amdgcn_s_setprio(0);
; template <class Epi>
; DEV void gemm_tile(const bf16_t* __restrict__ A, int lda, const bf16_t* __restrict__ Bt, int ldb, int K, int tm, int tn, char* smem, const Epi& epi) {
;     ...
;     const int nk = K >> 6;
;     G_DMA(0, 0);
;     asm volatile("s_waitcnt vmcnt(0)" ::: "memory");
;     __syncthreads();
; #pragma unroll 4
;     for (int kt = 0; kt < nk; ++kt) {
;         const int cur = kt & 1;
;         if (kt + 1 < nk) G_DMA(cur ^ 1, kt + 1);
;         {
;             G_FRAGS(cur, 0)
;             G_MMA(0)
;             G_FRAGS(cur, 1)
;             G_MMA(1)
;         }
;         asm volatile("s_waitcnt vmcnt(0)" ::: "memory");
;         __syncthreads();
;     }
	ds_read_b128 v[70:73], v89
	ds_read_b128 v[90:93], v89 offset:2048
	ds_read_b128 v[94:97], v89 offset:4096
	ds_read_b128 v[98:101], v89 offset:6144
	ds_read_b128 v[102:105], v151 offset:32768
	ds_read_b128 v[106:109], v151 offset:34816
	ds_read_b128 v[110:113], v151 offset:36864
	ds_read_b128 v[114:117], v151 offset:38912
	s_mov_b32 m0, s94
	v_mfma_f32_16x16x32_bf16 v[2:5], v[134:137], v[118:121], v[2:5]
	global_load_lds_dwordx4 v250, s[88:89]
	s_add_u32 m0, m0, 0x1000
	v_mfma_f32_16x16x32_bf16 v[6:9], v[138:141], v[118:121], v[6:9]
	global_load_lds_dwordx4 v249, s[88:89]
	s_add_u32 m0, m0, 0x1000
	v_mfma_f32_16x16x32_bf16 v[10:13], v[142:145], v[118:121], v[10:13]
	global_load_lds_dwordx4 v248, s[88:89]
	s_add_u32 m0, m0, 0x1000
	v_mfma_f32_16x16x32_bf16 v[14:17], v[146:149], v[118:121], v[14:17]
	global_load_lds_dwordx4 v247, s[88:89]
	s_add_u32 m0, m0, 0x5000
	v_mfma_f32_16x16x32_bf16 v[18:21], v[134:137], v[122:125], v[18:21]
	global_load_lds_dwordx4 v246, s[90:91]
	s_add_u32 m0, m0, 0x1000
	v_mfma_f32_16x16x32_bf16 v[22:25], v[138:141], v[122:125], v[22:25]
	global_load_lds_dwordx4 v245, s[90:91]
	s_add_u32 m0, m0, 0x1000
	v_mfma_f32_16x16x32_bf16 v[26:29], v[142:145], v[122:125], v[26:29]
	global_load_lds_dwordx4 v244, s[90:91]
	s_add_u32 m0, m0, 0x1000
	v_mfma_f32_16x16x32_bf16 v[30:33], v[146:149], v[122:125], v[30:33]
	global_load_lds_dwordx4 v243, s[90:91]
	v_mfma_f32_16x16x32_bf16 v[34:37], v[134:137], v[126:129], v[34:37]
	s_add_u32 s88, s88, 0x80
	v_mfma_f32_16x16x32_bf16 v[38:41], v[138:141], v[126:129], v[38:41]
	s_addc_u32 s89, s89, 0
	v_mfma_f32_16x16x32_bf16 v[42:45], v[142:145], v[126:129], v[42:45]
	s_add_u32 s90, s90, 0x80
	v_mfma_f32_16x16x32_bf16 v[46:49], v[146:149], v[126:129], v[46:49]
	s_addc_u32 s91, s91, 0
	v_mfma_f32_16x16x32_bf16 v[50:53], v[134:137], v[130:133], v[50:53]
	v_mfma_f32_16x16x32_bf16 v[54:57], v[138:141], v[130:133], v[54:57]
	v_mfma_f32_16x16x32_bf16 v[58:61], v[142:145], v[130:133], v[58:61]
	v_mfma_f32_16x16x32_bf16 v[62:65], v[146:149], v[130:133], v[62:65]
	s_sub_u32 s92, s92, 1
	s_cmp_lg_u32 s92, 0
	s_cbranch_scc1 .Lgemm_up_loop
	ds_read_b128 v[118:121], v150
	ds_read_b128 v[122:125], v150 offset:2048
	ds_read_b128 v[126:129], v150 offset:4096
	ds_read_b128 v[130:133], v150 offset:6144
	ds_read_b128 v[134:137], v152 offset:32768
	ds_read_b128 v[138:141], v152 offset:34816
	ds_read_b128 v[142:145], v152 offset:36864
	ds_read_b128 v[146:149], v152 offset:38912
	s_waitcnt lgkmcnt(8)
	v_mfma_f32_16x16x32_bf16 v[2:5], v[102:105], v[70:73], v[2:5]
	v_mfma_f32_16x16x32_bf16 v[6:9], v[106:109], v[70:73], v[6:9]
	v_mfma_f32_16x16x32_bf16 v[10:13], v[110:113], v[70:73], v[10:13]
	v_mfma_f32_16x16x32_bf16 v[14:17], v[114:117], v[70:73], v[14:17]
	v_mfma_f32_16x16x32_bf16 v[18:21], v[102:105], v[90:93], v[18:21]
	v_mfma_f32_16x16x32_bf16 v[22:25], v[106:109], v[90:93], v[22:25]
	v_mfma_f32_16x16x32_bf16 v[26:29], v[110:113], v[90:93], v[26:29]
	v_mfma_f32_16x16x32_bf16 v[30:33], v[114:117], v[90:93], v[30:33]
	v_mfma_f32_16x16x32_bf16 v[34:37], v[102:105], v[94:97], v[34:37]
	v_mfma_f32_16x16x32_bf16 v[38:41], v[106:109], v[94:97], v[38:41]
	v_mfma_f32_16x16x32_bf16 v[42:45], v[110:113], v[94:97], v[42:45]
	v_mfma_f32_16x16x32_bf16 v[46:49], v[114:117], v[94:97], v[46:49]
	v_mfma_f32_16x16x32_bf16 v[50:53], v[102:105], v[98:101], v[50:53]
	v_mfma_f32_16x16x32_bf16 v[54:57], v[106:109], v[98:101], v[54:57]
	v_mfma_f32_16x16x32_bf16 v[58:61], v[110:113], v[98:101], v[58:61]
	v_mfma_f32_16x16x32_bf16 v[62:65], v[114:117], v[98:101], v[62:65]
	s_waitcnt vmcnt(0) lgkmcnt(0)
	s_barrier
; #define G_MMA(ks_) __builtin_amdgcn_s_setprio(1); _Pragma("unroll") for (int m = 0; m < 4; ++m) \
;         _Pragma("unroll") for (int n = 0; n < 4; ++n) acc[m][n] = __builtin_amdgcn_mfma_f32_16x16x32_bf16(bfv##ks_[n], af##ks_[m], acc[m][n], 0, 0, 0); __builtin_amdgcn_s_setprio(0);
; template <class Epi>
; DEV void gemm_tile(const bf16_t* __restrict__ A, int lda, const bf16_t* __restrict__ Bt, int ldb, int K, int tm, int tn, char* smem, const Epi& epi) {
;     ...
;     const int nk = K >> 6;
;     G_DMA(0, 0);
;     asm volatile("s_waitcnt vmcnt(0)" ::: "memory");
;     __syncthreads();
; #pragma unroll 4
;     for (int kt = 0; kt < nk; ++kt) {
;         const int cur = kt & 1;
;         if (kt + 1 < nk) G_DMA(cur ^ 1, kt + 1);
;         {
;             G_FRAGS(cur, 0)
;             G_MMA(0)
;             G_FRAGS(cur, 1)
;             G_MMA(1)
;         }
;         asm volatile("s_waitcnt vmcnt(0)" ::: "memory");
;         __syncthreads();
;     }
	ds_read_b128 v[70:73], v89 offset:16384
	ds_read_b128 v[90:93], v89 offset:18432
	ds_read_b128 v[94:97], v89 offset:20480
	ds_read_b128 v[98:101], v89 offset:22528
	ds_read_b128 v[102:105], v151 offset:49152
	ds_read_b128 v[106:109], v151 offset:51200
	ds_read_b128 v[110:113], v151 offset:53248
	ds_read_b128 v[114:117], v151 offset:55296
	v_mfma_f32_16x16x32_bf16 v[2:5], v[134:137], v[118:121], v[2:5]
	v_mfma_f32_16x16x32_bf16 v[6:9], v[138:141], v[118:121], v[6:9]
	v_mfma_f32_16x16x32_bf16 v[10:13], v[142:145], v[118:121], v[10:13]
	v_mfma_f32_16x16x32_bf16 v[14:17], v[146:149], v[118:121], v[14:17]
	v_mfma_f32_16x16x32_bf16 v[18:21], v[134:137], v[122:125], v[18:21]
	v_mfma_f32_16x16x32_bf16 v[22:25], v[138:141], v[122:125], v[22:25]
	v_mfma_f32_16x16x32_bf16 v[26:29], v[142:145], v[122:125], v[26:29]
	v_mfma_f32_16x16x32_bf16 v[30:33], v[146:149], v[122:125], v[30:33]
	v_mfma_f32_16x16x32_bf16 v[34:37], v[134:137], v[126:129], v[34:37]
	v_mfma_f32_16x16x32_bf16 v[38:41], v[138:141], v[126:129], v[38:41]
	v_mfma_f32_16x16x32_bf16 v[42:45], v[142:145], v[126:129], v[42:45]
	v_mfma_f32_16x16x32_bf16 v[46:49], v[146:149], v[126:129], v[46:49]
	v_mfma_f32_16x16x32_bf16 v[50:53], v[134:137], v[130:133], v[50:53]
	v_mfma_f32_16x16x32_bf16 v[54:57], v[138:141], v[130:133], v[54:57]
	v_mfma_f32_16x16x32_bf16 v[58:61], v[142:145], v[130:133], v[58:61]
	v_mfma_f32_16x16x32_bf16 v[62:65], v[146:149], v[130:133], v[62:65]
	ds_read_b128 v[118:121], v150 offset:16384
	ds_read_b128 v[122:125], v150 offset:18432
	ds_read_b128 v[126:129], v150 offset:20480
	ds_read_b128 v[130:133], v150 offset:22528
	ds_read_b128 v[134:137], v152 offset:49152
	ds_read_b128 v[138:141], v152 offset:51200
	ds_read_b128 v[142:145], v152 offset:53248
	ds_read_b128 v[146:149], v152 offset:55296
	s_waitcnt lgkmcnt(8)
	v_mfma_f32_16x16x32_bf16 v[2:5], v[102:105], v[70:73], v[2:5]
	v_mfma_f32_16x16x32_bf16 v[6:9], v[106:109], v[70:73], v[6:9]
	v_mfma_f32_16x16x32_bf16 v[10:13], v[110:113], v[70:73], v[10:13]
	v_mfma_f32_16x16x32_bf16 v[14:17], v[114:117], v[70:73], v[14:17]
	v_mfma_f32_16x16x32_bf16 v[18:21], v[102:105], v[90:93], v[18:21]
	v_mfma_f32_16x16x32_bf16 v[22:25], v[106:109], v[90:93], v[22:25]
	v_mfma_f32_16x16x32_bf16 v[26:29], v[110:113], v[90:93], v[26:29]
	v_mfma_f32_16x16x32_bf16 v[30:33], v[114:117], v[90:93], v[30:33]
	v_mfma_f32_16x16x32_bf16 v[34:37], v[102:105], v[94:97], v[34:37]
	v_mfma_f32_16x16x32_bf16 v[38:41], v[106:109], v[94:97], v[38:41]
	v_mfma_f32_16x16x32_bf16 v[42:45], v[110:113], v[94:97], v[42:45]
	v_mfma_f32_16x16x32_bf16 v[46:49], v[114:117], v[94:97], v[46:49]
	v_mfma_f32_16x16x32_bf16 v[50:53], v[102:105], v[98:101], v[50:53]
	v_mfma_f32_16x16x32_bf16 v[54:57], v[106:109], v[98:101], v[54:57]
	v_mfma_f32_16x16x32_bf16 v[58:61], v[110:113], v[98:101], v[58:61]
	v_mfma_f32_16x16x32_bf16 v[62:65], v[114:117], v[98:101], v[62:65]
	s_waitcnt lgkmcnt(0)
	s_barrier
	v_mfma_f32_16x16x32_bf16 v[2:5], v[134:137], v[118:121], v[2:5]
	v_mfma_f32_16x16x32_bf16 v[6:9], v[138:141], v[118:121], v[6:9]
	v_mfma_f32_16x16x32_bf16 v[10:13], v[142:145], v[118:121], v[10:13]
	v_mfma_f32_16x16x32_bf16 v[14:17], v[146:149], v[118:121], v[14:17]
	v_mfma_f32_16x16x32_bf16 v[18:21], v[134:137], v[122:125], v[18:21]
	v_mfma_f32_16x16x32_bf16 v[22:25], v[138:141], v[122:125], v[22:25]
	v_mfma_f32_16x16x32_bf16 v[26:29], v[142:145], v[122:125], v[26:29]
	v_mfma_f32_16x16x32_bf16 v[30:33], v[146:149], v[122:125], v[30:33]
	v_mfma_f32_16x16x32_bf16 v[34:37], v[134:137], v[126:129], v[34:37]
	v_mfma_f32_16x16x32_bf16 v[38:41], v[138:141], v[126:129], v[38:41]
	v_mfma_f32_16x16x32_bf16 v[42:45], v[142:145], v[126:129], v[42:45]
	v_mfma_f32_16x16x32_bf16 v[46:49], v[146:149], v[126:129], v[46:49]
	v_mfma_f32_16x16x32_bf16 v[50:53], v[134:137], v[130:133], v[50:53]
	v_mfma_f32_16x16x32_bf16 v[54:57], v[138:141], v[130:133], v[54:57]
	v_mfma_f32_16x16x32_bf16 v[58:61], v[142:145], v[130:133], v[58:61]
	v_mfma_f32_16x16x32_bf16 v[62:65], v[146:149], v[130:133], v[62:65]
	s_setprio 0
	v_readlane_b32 s88, v255, 24
	v_readlane_b32 s89, v255, 25
	v_readlane_b32 s90, v255, 26
	v_readlane_b32 s91, v255, 27
	v_readlane_b32 s92, v255, 28
	v_readlane_b32 s93, v255, 29
	v_readlane_b32 s94, v255, 30
	v_readlane_b32 s95, v255, 31
	s_nop 7
	s_nop 1

; template <class Epi>
; DEV void gemm_tile(const bf16_t* __restrict__ A, int lda, const bf16_t* __restrict__ Bt, int ldb, int K, int tm, int tn, char* smem, const Epi& epi) {
;     ...
;     const int lrow = tid >> 3, lcc = (tid & 7) * 8, lsw = (((tid & 7) ^ (lrow & 7)) * 8);
;     const bf16_t* Ag = A + (size_t)(tm * 128 + lrow) * lda + lcc;
;     const bf16_t* Bg = Bt + (size_t)(tn * 128 + lrow) * ldb + lcc;
;     f32x4 acc[4][4];
; #pragma unroll
;     for (int m = 0; m < 4; ++m)
; #pragma unroll
;         for (int n = 0; n < 4; ++n) acc[m][n] = (f32x4){0.f, 0.f, 0.f, 0.f};
;     const int gsw = (((tid & 7) ^ (lrow & 7)) * 8);
;     const bf16_t* Ad = A + (size_t)(tm * 128 + lrow) * lda + gsw;
;     const bf16_t* Bd = Bt + (size_t)(tn * 128 + lrow) * ldb + gsw;
;     char* Asb = (char*)As; char* Bsb = (char*)Bs;
;     ...
;     const int nk = K >> 6;
;     G_DMA(0, 0);
;     asm volatile("s_waitcnt vmcnt(0)" ::: "memory");
;     __syncthreads();
; template <class Epi>
; DEV void gemm_phase(const bf16_t* A, int lda, const bf16_t* Bt, int ldb, int K, int ntm, int ntn, bool skip_ctx, char* smem, const Epi& epi) {
;     ...
;         for (int q = slot; q < per; q += nper) {
;             int tm, tn;
;             if (q < fullq) { const int tb = q / (R * 8), r = q - tb * (R * 8); tm = r >> 3; tn = tb * 8 + (r & 7); }
;             else { const int q2 = q - fullq; tm = q2 / w; tn = nfb * 8 + (q2 - tm * w); }
;             tm += xcd * R;
;             if (skip_ctx && ((tm * 128) % TT) >= SEQ) continue;
;             gemm_tile(A, lda, Bt, ldb, K, tm, tn, smem, epi);
.LBB0_162:
	s_lshr_b32 s43, s37, 3
	v_readlane_b32 s42, v253, 31
	s_add_i32 s43, s43, s42
	s_lshl_b32 s42, s43, 7
	s_mul_hi_u32 s44, s42, 0x38e38e39
	s_lshr_b32 s44, s44, 9
	s_mulk_i32 s44, 0x900
	s_sub_i32 s44, s42, s44
	s_cmpk_gt_u32 s44, 0x7ff
	s_cselect_b64 s[44:45], -1, 0
	s_and_b64 s[44:45], s[54:55], s[44:45]
	s_and_b64 vcc, exec, s[44:45]
	s_cbranch_vccnz .LBB0_161
	v_mov_b32_e32 v10, v163
	s_and_b32 s44, s36, 0x380
	s_waitcnt vmcnt(10)
	v_ashrrev_i32_e32 v0, 3, v10
	v_add_u32_e32 v2, s42, v0
	v_ashrrev_i32_e32 v3, 31, v2
	v_add_u32_e32 v4, s44, v0
	v_xor_b32_e32 v0, v0, v10
	v_ashrrev_i32_e32 v5, 31, v4
	v_lshlrev_b64 v[2:3], 11, v[2:3]
	v_lshlrev_b32_e32 v0, 4, v0
	s_waitcnt vmcnt(5)
	v_lshl_add_u32 v22, v10, 4, 16
	v_lshl_add_u64 v[2:3], s[26:27], 0, v[2:3]
	v_lshlrev_b64 v[4:5], 11, v[4:5]
	v_and_b32_e32 v0, 0x70, v0
	s_waitcnt vmcnt(4)
	v_add_u32_e32 v21, 0x8000, v22
	v_readfirstlane_b32 s65, v22
	v_lshl_add_u64 v[8:9], s[38:39], 0, v[4:5]
	v_lshl_add_u64 v[4:5], v[2:3], 0, v[0:1]
	s_mov_b32 m0, s65
	v_readfirstlane_b32 s53, v21
	v_add_u32_e32 v23, 0x1000, v22
	v_lshl_add_u64 v[2:3], v[8:9], 0, v[0:1]
	global_load_lds_dwordx4 v[4:5], off
	s_mov_b32 m0, s53
	s_mov_b64 s[90:91], 0x10000
	v_readfirstlane_b32 s62, v23
	v_add_u32_e32 v24, 0x9000, v22
	global_load_lds_dwordx4 v[2:3], off
	v_lshl_add_u64 v[8:9], v[4:5], 0, s[90:91]
	s_mov_b32 m0, s62
	v_readfirstlane_b32 s63, v24
	v_add_u32_e32 v25, 0x2000, v22
	global_load_lds_dwordx4 v[8:9], off
	v_lshl_add_u64 v[8:9], v[2:3], 0, s[90:91]
	s_mov_b32 m0, s63
	s_mov_b64 s[92:93], 0x20000
	v_readfirstlane_b32 s64, v25
	v_add_u32_e32 v26, 0xa000, v22
	global_load_lds_dwordx4 v[8:9], off
	v_lshl_add_u64 v[8:9], v[4:5], 0, s[92:93]
	s_mov_b32 m0, s64
	v_readfirstlane_b32 s84, v26
	v_add_u32_e32 v27, 0x3000, v22
	global_load_lds_dwordx4 v[8:9], off
	v_lshl_add_u64 v[8:9], v[2:3], 0, s[92:93]
	s_mov_b32 m0, s84
	s_mov_b64 s[0:1], 0x30000
	v_readfirstlane_b32 s85, v27
	v_add_u32_e32 v28, 0xb000, v22
	global_load_lds_dwordx4 v[8:9], off
	v_lshl_add_u64 v[8:9], v[4:5], 0, s[0:1]
	s_mov_b32 m0, s85
	v_readfirstlane_b32 s86, v28
	global_load_lds_dwordx4 v[8:9], off
	v_lshl_add_u64 v[8:9], v[2:3], 0, s[0:1]
	s_mov_b32 m0, s86
	v_and_b32_e32 v7, 15, v10
	global_load_lds_dwordx4 v[8:9], off
	v_ashrrev_i32_e32 v8, 7, v10
	v_lshlrev_b32_e32 v9, 13, v8
	v_lshlrev_b32_e32 v12, 7, v7
	v_bfe_u32 v6, v10, 6, 1
	v_lshrrev_b32_e32 v11, 4, v10
	v_add3_u32 v29, 16, v9, v12
	v_and_b32_e32 v9, 7, v10
	v_bfe_u32 v0, v10, 4, 2
	v_bitop3_b32 v10, v11, v9, 3 bitop3:0x6c
	v_lshlrev_b32_e32 v11, 13, v6
	v_add3_u32 v110, 16, v11, v12
	v_add_u32_e32 v11, 0x4000, v22
	s_mov_b64 s[46:47], 0x80
	v_add_u32_e32 v12, 0xc000, v22
	v_readfirstlane_b32 s49, v11
	v_lshl_add_u64 v[14:15], v[4:5], 0, s[46:47]
	s_mov_b32 m0, s49
	v_readfirstlane_b32 s45, v12
	v_add_u32_e32 v13, 0x5000, v22
	s_waitcnt vmcnt(0)
	s_waitcnt vmcnt(0) lgkmcnt(0)
	s_barrier
	v_writelane_b32 v255, s88, 24
	v_writelane_b32 v255, s89, 25
	v_writelane_b32 v255, s90, 26
	v_writelane_b32 v255, s91, 27
	v_writelane_b32 v255, s92, 28
	v_writelane_b32 v255, s93, 29
	v_writelane_b32 v255, s94, 30
	v_writelane_b32 v255, s95, 31
	v_readfirstlane_b32 s88, v4
	v_readfirstlane_b32 s89, v5
	v_readfirstlane_b32 s90, v2
	v_readfirstlane_b32 s91, v3
	v_lshl_add_u32 v242, v163, 4, 16
	s_and_b32 s88, s88, 0xffffff80
	s_and_b32 s90, s90, 0xffffff80
	v_readfirstlane_b32 s93, v242
	v_subrev_u32_e32 v250, s88, v4
	v_subrev_u32_e32 v246, s90, v2
	v_add_u32_e32 v249, 0x10000, v250
	v_add_u32_e32 v245, 0x10000, v246
	v_add_u32_e32 v248, 0x20000, v250
	v_add_u32_e32 v244, 0x20000, v246
	v_add_u32_e32 v247, 0x30000, v250
	v_add_u32_e32 v243, 0x30000, v246
	s_add_u32 s94, s93, 0x4000
	s_add_u32 s88, s88, 0x80
	s_addc_u32 s89, s89, 0
	s_add_u32 s90, s90, 0x80
	s_addc_u32 s91, s91, 0
	v_and_b32_e32 v242, 15, v163
	v_lshlrev_b32_e32 v242, 7, v242
	v_bfe_u32 v217, v163, 4, 2
	v_and_b32_e32 v218, 7, v163
	v_xor_b32_e32 v217, v217, v218
	v_lshlrev_b32_e32 v218, 4, v217
	v_xor_b32_e32 v217, 4, v217
	v_lshlrev_b32_e32 v217, 4, v217
	v_lshrrev_b32_e32 v184, 7, v163
	v_lshl_add_u32 v184, v184, 13, v242
	v_add_u32_e32 v184, 16, v184
	v_bfe_u32 v215, v163, 6, 1
	v_lshl_add_u32 v215, v215, 13, v242
	v_add_u32_e32 v215, 16, v215
	v_add_u32_e32 v214, v184, v217
	v_add_u32_e32 v216, v215, v217
	v_add_u32_e32 v184, v184, v218
	v_add_u32_e32 v215, v215, v218
	v_mov_b32_e32 v62, 0
	v_mov_b32_e32 v63, 0
	v_mov_b32_e32 v64, 0
	v_mov_b32_e32 v65, 0
	v_mov_b32_e32 v66, 0
	v_mov_b32_e32 v67, 0
	v_mov_b32_e32 v68, 0
	v_mov_b32_e32 v69, 0
	v_mov_b32_e32 v70, 0
	v_mov_b32_e32 v71, 0
	v_mov_b32_e32 v72, 0
	v_mov_b32_e32 v73, 0
	v_mov_b32_e32 v2, 0
	v_mov_b32_e32 v3, 0
	v_mov_b32_e32 v4, 0
	v_mov_b32_e32 v5, 0
	v_mov_b32_e32 v18, 0
	v_mov_b32_e32 v19, 0
	v_mov_b32_e32 v20, 0
	v_mov_b32_e32 v21, 0
	v_mov_b32_e32 v28, 0
	v_mov_b32_e32 v29, 0
	v_mov_b32_e32 v30, 0
	v_mov_b32_e32 v31, 0
	v_mov_b32_e32 v56, 0
	v_mov_b32_e32 v57, 0
	v_mov_b32_e32 v58, 0
	v_mov_b32_e32 v59, 0
	v_mov_b32_e32 v10, 0
	v_mov_b32_e32 v11, 0
	v_mov_b32_e32 v12, 0
	v_mov_b32_e32 v13, 0
	v_mov_b32_e32 v22, 0
	v_mov_b32_e32 v23, 0
	v_mov_b32_e32 v24, 0
	v_mov_b32_e32 v25, 0
	v_mov_b32_e32 v32, 0
	v_mov_b32_e32 v33, 0
	v_mov_b32_e32 v34, 0
	v_mov_b32_e32 v35, 0
	v_mov_b32_e32 v74, 0
	v_mov_b32_e32 v75, 0
	v_mov_b32_e32 v76, 0
	v_mov_b32_e32 v77, 0
	v_mov_b32_e32 v36, 0
	v_mov_b32_e32 v37, 0
	v_mov_b32_e32 v38, 0
	v_mov_b32_e32 v39, 0
	v_mov_b32_e32 v44, 0
	v_mov_b32_e32 v45, 0
	v_mov_b32_e32 v46, 0
	v_mov_b32_e32 v47, 0
	v_mov_b32_e32 v48, 0
	v_mov_b32_e32 v49, 0
	v_mov_b32_e32 v50, 0
	v_mov_b32_e32 v51, 0
	v_mov_b32_e32 v52, 0
	v_mov_b32_e32 v53, 0
	v_mov_b32_e32 v54, 0
	v_mov_b32_e32 v55, 0
	v_mov_b32_e32 v14, 0
	v_mov_b32_e32 v15, 0
	v_mov_b32_e32 v16, 0
	v_mov_b32_e32 v17, 0
	s_mov_b32 m0, s94
	s_nop 0
	global_load_lds_dwordx4 v250, s[88:89]
	s_add_u32 m0, m0, 0x1000
	s_nop 0
	global_load_lds_dwordx4 v249, s[88:89]
	s_add_u32 m0, m0, 0x1000
	s_nop 0
	global_load_lds_dwordx4 v248, s[88:89]
	s_add_u32 m0, m0, 0x1000
	s_nop 0
	global_load_lds_dwordx4 v247, s[88:89]
	s_add_u32 m0, m0, 0x5000
	s_nop 0
	global_load_lds_dwordx4 v246, s[90:91]
	s_add_u32 m0, m0, 0x1000
	s_nop 0
	global_load_lds_dwordx4 v245, s[90:91]
	s_add_u32 m0, m0, 0x1000
	s_nop 0
	global_load_lds_dwordx4 v244, s[90:91]
	s_add_u32 m0, m0, 0x1000
	s_nop 0
	global_load_lds_dwordx4 v243, s[90:91]
	s_add_u32 s88, s88, 0x80
	s_addc_u32 s89, s89, 0
	s_add_u32 s90, s90, 0x80
	s_addc_u32 s91, s91, 0
	ds_read_b128 v[126:129], v184
	ds_read_b128 v[130:133], v184 offset:2048
	ds_read_b128 v[134:137], v184 offset:4096
	ds_read_b128 v[138:141], v184 offset:6144
	ds_read_b128 v[142:145], v215 offset:32768
	ds_read_b128 v[146:149], v215 offset:34816
	ds_read_b128 v[150:153], v215 offset:36864
	ds_read_b128 v[154:157], v215 offset:38912
	v_readlane_b32 s95, v251, 0
	s_nop 0
	s_cmp_lt_u32 s95, 0x100
	s_setprio 1
	s_cbranch_scc1 .Lgemm_out_lowprio
	s_setprio 2

; #define G_MMA(ks_) __builtin_amdgcn_s_setprio(1); _Pragma("unroll") for (int m = 0; m < 4; ++m) \
;         _Pragma("unroll") for (int n = 0; n < 4; ++n) acc[m][n] = __builtin_amdgcn_mfma_f32_16x16x32_bf16(bfv##ks_[n], af##ks_[m], acc[m][n], 0, 0, 0); __builtin_amdgcn_s_setprio(0);
; template <class Epi>
; DEV void gemm_tile(const bf16_t* __restrict__ A, int lda, const bf16_t* __restrict__ Bt, int ldb, int K, int tm, int tn, char* smem, const Epi& epi) {
;     ...
;     const int nk = K >> 6;
;     G_DMA(0, 0);
;     asm volatile("s_waitcnt vmcnt(0)" ::: "memory");
;     __syncthreads();
; #pragma unroll 4
;     for (int kt = 0; kt < nk; ++kt) {
;         const int cur = kt & 1;
;         if (kt + 1 < nk) G_DMA(cur ^ 1, kt + 1);
;         {
;             G_FRAGS(cur, 0)
;             G_MMA(0)
;             G_FRAGS(cur, 1)
;             G_MMA(1)
;         }
;         asm volatile("s_waitcnt vmcnt(0)" ::: "memory");
;         __syncthreads();
;     }
.Lgemm_out_loop:
	ds_read_b128 v[158:161], v214
	ds_read_b128 v[164:167], v214 offset:2048
	ds_read_b128 v[168:171], v214 offset:4096
	ds_read_b128 v[172:175], v214 offset:6144
	ds_read_b128 v[176:179], v216 offset:32768
	ds_read_b128 v[180:183], v216 offset:34816
	ds_read_b128 v[192:195], v216 offset:36864
	ds_read_b128 v[210:213], v216 offset:38912
	s_waitcnt lgkmcnt(8)
	v_mfma_f32_16x16x32_bf16 v[62:65], v[142:145], v[126:129], v[62:65]
	v_mfma_f32_16x16x32_bf16 v[66:69], v[146:149], v[126:129], v[66:69]
	v_mfma_f32_16x16x32_bf16 v[70:73], v[150:153], v[126:129], v[70:73]
	v_mfma_f32_16x16x32_bf16 v[2:5], v[154:157], v[126:129], v[2:5]
	v_mfma_f32_16x16x32_bf16 v[18:21], v[142:145], v[130:133], v[18:21]
	v_mfma_f32_16x16x32_bf16 v[28:31], v[146:149], v[130:133], v[28:31]
	v_mfma_f32_16x16x32_bf16 v[56:59], v[150:153], v[130:133], v[56:59]
	v_mfma_f32_16x16x32_bf16 v[10:13], v[154:157], v[130:133], v[10:13]
	v_mfma_f32_16x16x32_bf16 v[22:25], v[142:145], v[134:137], v[22:25]
	v_mfma_f32_16x16x32_bf16 v[32:35], v[146:149], v[134:137], v[32:35]
	v_mfma_f32_16x16x32_bf16 v[74:77], v[150:153], v[134:137], v[74:77]
	v_mfma_f32_16x16x32_bf16 v[36:39], v[154:157], v[134:137], v[36:39]
	v_mfma_f32_16x16x32_bf16 v[44:47], v[142:145], v[138:141], v[44:47]
	v_mfma_f32_16x16x32_bf16 v[48:51], v[146:149], v[138:141], v[48:51]
	v_mfma_f32_16x16x32_bf16 v[52:55], v[150:153], v[138:141], v[52:55]
	v_mfma_f32_16x16x32_bf16 v[14:17], v[154:157], v[138:141], v[14:17]
	s_waitcnt vmcnt(0) lgkmcnt(0)
	s_barrier
	ds_read_b128 v[126:129], v184 offset:16384
	ds_read_b128 v[130:133], v184 offset:18432
	ds_read_b128 v[134:137], v184 offset:20480
	ds_read_b128 v[138:141], v184 offset:22528
	ds_read_b128 v[142:145], v215 offset:49152
	ds_read_b128 v[146:149], v215 offset:51200
	ds_read_b128 v[150:153], v215 offset:53248
	ds_read_b128 v[154:157], v215 offset:55296
	s_mov_b32 m0, s93
	v_mfma_f32_16x16x32_bf16 v[62:65], v[176:179], v[158:161], v[62:65]
	global_load_lds_dwordx4 v250, s[88:89]
	s_add_u32 m0, m0, 0x1000
	v_mfma_f32_16x16x32_bf16 v[66:69], v[180:183], v[158:161], v[66:69]
	global_load_lds_dwordx4 v249, s[88:89]
	s_add_u32 m0, m0, 0x1000
	v_mfma_f32_16x16x32_bf16 v[70:73], v[192:195], v[158:161], v[70:73]
	global_load_lds_dwordx4 v248, s[88:89]
	s_add_u32 m0, m0, 0x1000
	v_mfma_f32_16x16x32_bf16 v[2:5], v[210:213], v[158:161], v[2:5]
	global_load_lds_dwordx4 v247, s[88:89]
	s_add_u32 m0, m0, 0x5000
	v_mfma_f32_16x16x32_bf16 v[18:21], v[176:179], v[164:167], v[18:21]
	global_load_lds_dwordx4 v246, s[90:91]
	s_add_u32 m0, m0, 0x1000
	v_mfma_f32_16x16x32_bf16 v[28:31], v[180:183], v[164:167], v[28:31]
	global_load_lds_dwordx4 v245, s[90:91]
	s_add_u32 m0, m0, 0x1000
	v_mfma_f32_16x16x32_bf16 v[56:59], v[192:195], v[164:167], v[56:59]
	global_load_lds_dwordx4 v244, s[90:91]
	s_add_u32 m0, m0, 0x1000
	v_mfma_f32_16x16x32_bf16 v[10:13], v[210:213], v[164:167], v[10:13]
	global_load_lds_dwordx4 v243, s[90:91]
	v_mfma_f32_16x16x32_bf16 v[22:25], v[176:179], v[168:171], v[22:25]
	s_add_u32 s88, s88, 0x80
	v_mfma_f32_16x16x32_bf16 v[32:35], v[180:183], v[168:171], v[32:35]
	s_addc_u32 s89, s89, 0
	v_mfma_f32_16x16x32_bf16 v[74:77], v[192:195], v[168:171], v[74:77]
	s_add_u32 s90, s90, 0x80
	v_mfma_f32_16x16x32_bf16 v[36:39], v[210:213], v[168:171], v[36:39]
	s_addc_u32 s91, s91, 0
	v_mfma_f32_16x16x32_bf16 v[44:47], v[176:179], v[172:175], v[44:47]
	v_mfma_f32_16x16x32_bf16 v[48:51], v[180:183], v[172:175], v[48:51]
	v_mfma_f32_16x16x32_bf16 v[52:55], v[192:195], v[172:175], v[52:55]
	v_mfma_f32_16x16x32_bf16 v[14:17], v[210:213], v[172:175], v[14:17]
	ds_read_b128 v[158:161], v214 offset:16384
	ds_read_b128 v[164:167], v214 offset:18432
	ds_read_b128 v[168:171], v214 offset:20480
	ds_read_b128 v[172:175], v214 offset:22528
	ds_read_b128 v[176:179], v216 offset:49152
	ds_read_b128 v[180:183], v216 offset:51200
	ds_read_b128 v[192:195], v216 offset:53248
	ds_read_b128 v[210:213], v216 offset:55296
	s_waitcnt lgkmcnt(8)
	v_mfma_f32_16x16x32_bf16 v[62:65], v[142:145], v[126:129], v[62:65]
	v_mfma_f32_16x16x32_bf16 v[66:69], v[146:149], v[126:129], v[66:69]
	v_mfma_f32_16x16x32_bf16 v[70:73], v[150:153], v[126:129], v[70:73]
	v_mfma_f32_16x16x32_bf16 v[2:5], v[154:157], v[126:129], v[2:5]
	v_mfma_f32_16x16x32_bf16 v[18:21], v[142:145], v[130:133], v[18:21]
	v_mfma_f32_16x16x32_bf16 v[28:31], v[146:149], v[130:133], v[28:31]
	v_mfma_f32_16x16x32_bf16 v[56:59], v[150:153], v[130:133], v[56:59]
	v_mfma_f32_16x16x32_bf16 v[10:13], v[154:157], v[130:133], v[10:13]
	v_mfma_f32_16x16x32_bf16 v[22:25], v[142:145], v[134:137], v[22:25]
	v_mfma_f32_16x16x32_bf16 v[32:35], v[146:149], v[134:137], v[32:35]
	v_mfma_f32_16x16x32_bf16 v[74:77], v[150:153], v[134:137], v[74:77]
	v_mfma_f32_16x16x32_bf16 v[36:39], v[154:157], v[134:137], v[36:39]
	v_mfma_f32_16x16x32_bf16 v[44:47], v[142:145], v[138:141], v[44:47]
	v_mfma_f32_16x16x32_bf16 v[48:51], v[146:149], v[138:141], v[48:51]
	v_mfma_f32_16x16x32_bf16 v[52:55], v[150:153], v[138:141], v[52:55]
	v_mfma_f32_16x16x32_bf16 v[14:17], v[154:157], v[138:141], v[14:17]
	s_waitcnt vmcnt(0) lgkmcnt(0)
	s_barrier
; #define G_MMA(ks_) __builtin_amdgcn_s_setprio(1); _Pragma("unroll") for (int m = 0; m < 4; ++m) \
;         _Pragma("unroll") for (int n = 0; n < 4; ++n) acc[m][n] = __builtin_amdgcn_mfma_f32_16x16x32_bf16(bfv##ks_[n], af##ks_[m], acc[m][n], 0, 0, 0); __builtin_amdgcn_s_setprio(0);
; template <class Epi>
; DEV void gemm_tile(const bf16_t* __restrict__ A, int lda, const bf16_t* __restrict__ Bt, int ldb, int K, int tm, int tn, char* smem, const Epi& epi) {
;     ...
;     const int nk = K >> 6;
;     G_DMA(0, 0);
;     asm volatile("s_waitcnt vmcnt(0)" ::: "memory");
;     __syncthreads();
; #pragma unroll 4
;     for (int kt = 0; kt < nk; ++kt) {
;         const int cur = kt & 1;
;         if (kt + 1 < nk) G_DMA(cur ^ 1, kt + 1);
;         {
;             G_FRAGS(cur, 0)
;             G_MMA(0)
;             G_FRAGS(cur, 1)
;             G_MMA(1)
;         }
;         asm volatile("s_waitcnt vmcnt(0)" ::: "memory");
;         __syncthreads();
;     }
	ds_read_b128 v[126:129], v184
	ds_read_b128 v[130:133], v184 offset:2048
	ds_read_b128 v[134:137], v184 offset:4096
	ds_read_b128 v[138:141], v184 offset:6144
	ds_read_b128 v[142:145], v215 offset:32768
	ds_read_b128 v[146:149], v215 offset:34816
	ds_read_b128 v[150:153], v215 offset:36864
	ds_read_b128 v[154:157], v215 offset:38912
	s_mov_b32 m0, s94
	v_mfma_f32_16x16x32_bf16 v[62:65], v[176:179], v[158:161], v[62:65]
	global_load_lds_dwordx4 v250, s[88:89]
	s_add_u32 m0, m0, 0x1000
	v_mfma_f32_16x16x32_bf16 v[66:69], v[180:183], v[158:161], v[66:69]
	global_load_lds_dwordx4 v249, s[88:89]
	s_add_u32 m0, m0, 0x1000
	v_mfma_f32_16x16x32_bf16 v[70:73], v[192:195], v[158:161], v[70:73]
	global_load_lds_dwordx4 v248, s[88:89]
	s_add_u32 m0, m0, 0x1000
	v_mfma_f32_16x16x32_bf16 v[2:5], v[210:213], v[158:161], v[2:5]
	global_load_lds_dwordx4 v247, s[88:89]
	s_add_u32 m0, m0, 0x5000
	v_mfma_f32_16x16x32_bf16 v[18:21], v[176:179], v[164:167], v[18:21]
	global_load_lds_dwordx4 v246, s[90:91]
	s_add_u32 m0, m0, 0x1000
	v_mfma_f32_16x16x32_bf16 v[28:31], v[180:183], v[164:167], v[28:31]
	global_load_lds_dwordx4 v245, s[90:91]
	s_add_u32 m0, m0, 0x1000
	v_mfma_f32_16x16x32_bf16 v[56:59], v[192:195], v[164:167], v[56:59]
	global_load_lds_dwordx4 v244, s[90:91]
	s_add_u32 m0, m0, 0x1000
	v_mfma_f32_16x16x32_bf16 v[10:13], v[210:213], v[164:167], v[10:13]
	global_load_lds_dwordx4 v243, s[90:91]
	v_mfma_f32_16x16x32_bf16 v[22:25], v[176:179], v[168:171], v[22:25]
	s_add_u32 s88, s88, 0x80
	v_mfma_f32_16x16x32_bf16 v[32:35], v[180:183], v[168:171], v[32:35]
	s_addc_u32 s89, s89, 0
	v_mfma_f32_16x16x32_bf16 v[74:77], v[192:195], v[168:171], v[74:77]
	s_add_u32 s90, s90, 0x80
	v_mfma_f32_16x16x32_bf16 v[36:39], v[210:213], v[168:171], v[36:39]
	s_addc_u32 s91, s91, 0
	v_mfma_f32_16x16x32_bf16 v[44:47], v[176:179], v[172:175], v[44:47]
	v_mfma_f32_16x16x32_bf16 v[48:51], v[180:183], v[172:175], v[48:51]
	v_mfma_f32_16x16x32_bf16 v[52:55], v[192:195], v[172:175], v[52:55]
	v_mfma_f32_16x16x32_bf16 v[14:17], v[210:213], v[172:175], v[14:17]
	s_sub_u32 s92, s92, 1
	s_cmp_lg_u32 s92, 0
	s_cbranch_scc1 .Lgemm_out_loop
	ds_read_b128 v[158:161], v214
	ds_read_b128 v[164:167], v214 offset:2048
	ds_read_b128 v[168:171], v214 offset:4096
	ds_read_b128 v[172:175], v214 offset:6144
	ds_read_b128 v[176:179], v216 offset:32768
	ds_read_b128 v[180:183], v216 offset:34816
	ds_read_b128 v[192:195], v216 offset:36864
	ds_read_b128 v[210:213], v216 offset:38912
	s_waitcnt lgkmcnt(8)
	v_mfma_f32_16x16x32_bf16 v[62:65], v[142:145], v[126:129], v[62:65]
	v_mfma_f32_16x16x32_bf16 v[66:69], v[146:149], v[126:129], v[66:69]
	v_mfma_f32_16x16x32_bf16 v[70:73], v[150:153], v[126:129], v[70:73]
	v_mfma_f32_16x16x32_bf16 v[2:5], v[154:157], v[126:129], v[2:5]
	v_mfma_f32_16x16x32_bf16 v[18:21], v[142:145], v[130:133], v[18:21]
	v_mfma_f32_16x16x32_bf16 v[28:31], v[146:149], v[130:133], v[28:31]
	v_mfma_f32_16x16x32_bf16 v[56:59], v[150:153], v[130:133], v[56:59]
	v_mfma_f32_16x16x32_bf16 v[10:13], v[154:157], v[130:133], v[10:13]
	v_mfma_f32_16x16x32_bf16 v[22:25], v[142:145], v[134:137], v[22:25]
	v_mfma_f32_16x16x32_bf16 v[32:35], v[146:149], v[134:137], v[32:35]
	v_mfma_f32_16x16x32_bf16 v[74:77], v[150:153], v[134:137], v[74:77]
	v_mfma_f32_16x16x32_bf16 v[36:39], v[154:157], v[134:137], v[36:39]
	v_mfma_f32_16x16x32_bf16 v[44:47], v[142:145], v[138:141], v[44:47]
	v_mfma_f32_16x16x32_bf16 v[48:51], v[146:149], v[138:141], v[48:51]
	v_mfma_f32_16x16x32_bf16 v[52:55], v[150:153], v[138:141], v[52:55]
	v_mfma_f32_16x16x32_bf16 v[14:17], v[154:157], v[138:141], v[14:17]
	s_waitcnt vmcnt(0) lgkmcnt(0)
	s_barrier
	ds_read_b128 v[126:129], v184 offset:16384
	ds_read_b128 v[130:133], v184 offset:18432
	ds_read_b128 v[134:137], v184 offset:20480
	ds_read_b128 v[138:141], v184 offset:22528
	ds_read_b128 v[142:145], v215 offset:49152
	ds_read_b128 v[146:149], v215 offset:51200
	ds_read_b128 v[150:153], v215 offset:53248
	ds_read_b128 v[154:157], v215 offset:55296
	v_mfma_f32_16x16x32_bf16 v[62:65], v[176:179], v[158:161], v[62:65]
	v_mfma_f32_16x16x32_bf16 v[66:69], v[180:183], v[158:161], v[66:69]
	v_mfma_f32_16x16x32_bf16 v[70:73], v[192:195], v[158:161], v[70:73]
	v_mfma_f32_16x16x32_bf16 v[2:5], v[210:213], v[158:161], v[2:5]
	v_mfma_f32_16x16x32_bf16 v[18:21], v[176:179], v[164:167], v[18:21]
	v_mfma_f32_16x16x32_bf16 v[28:31], v[180:183], v[164:167], v[28:31]
	v_mfma_f32_16x16x32_bf16 v[56:59], v[192:195], v[164:167], v[56:59]
	v_mfma_f32_16x16x32_bf16 v[10:13], v[210:213], v[164:167], v[10:13]
	v_mfma_f32_16x16x32_bf16 v[22:25], v[176:179], v[168:171], v[22:25]
	v_mfma_f32_16x16x32_bf16 v[32:35], v[180:183], v[168:171], v[32:35]
	v_mfma_f32_16x16x32_bf16 v[74:77], v[192:195], v[168:171], v[74:77]
	v_mfma_f32_16x16x32_bf16 v[36:39], v[210:213], v[168:171], v[36:39]
	v_mfma_f32_16x16x32_bf16 v[44:47], v[176:179], v[172:175], v[44:47]
	v_mfma_f32_16x16x32_bf16 v[48:51], v[180:183], v[172:175], v[48:51]
	v_mfma_f32_16x16x32_bf16 v[52:55], v[192:195], v[172:175], v[52:55]
	v_mfma_f32_16x16x32_bf16 v[14:17], v[210:213], v[172:175], v[14:17]
	ds_read_b128 v[158:161], v214 offset:16384
	ds_read_b128 v[164:167], v214 offset:18432
	ds_read_b128 v[168:171], v214 offset:20480
	ds_read_b128 v[172:175], v214 offset:22528
	ds_read_b128 v[176:179], v216 offset:49152
	ds_read_b128 v[180:183], v216 offset:51200
	ds_read_b128 v[192:195], v216 offset:53248
	ds_read_b128 v[210:213], v216 offset:55296
	s_waitcnt lgkmcnt(8)
	v_mfma_f32_16x16x32_bf16 v[62:65], v[142:145], v[126:129], v[62:65]
	v_mfma_f32_16x16x32_bf16 v[66:69], v[146:149], v[126:129], v[66:69]
	v_mfma_f32_16x16x32_bf16 v[70:73], v[150:153], v[126:129], v[70:73]
	v_mfma_f32_16x16x32_bf16 v[2:5], v[154:157], v[126:129], v[2:5]
	v_mfma_f32_16x16x32_bf16 v[18:21], v[142:145], v[130:133], v[18:21]
	v_mfma_f32_16x16x32_bf16 v[28:31], v[146:149], v[130:133], v[28:31]
	v_mfma_f32_16x16x32_bf16 v[56:59], v[150:153], v[130:133], v[56:59]
	v_mfma_f32_16x16x32_bf16 v[10:13], v[154:157], v[130:133], v[10:13]
	v_mfma_f32_16x16x32_bf16 v[22:25], v[142:145], v[134:137], v[22:25]
	v_mfma_f32_16x16x32_bf16 v[32:35], v[146:149], v[134:137], v[32:35]
	v_mfma_f32_16x16x32_bf16 v[74:77], v[150:153], v[134:137], v[74:77]
	v_mfma_f32_16x16x32_bf16 v[36:39], v[154:157], v[134:137], v[36:39]
	v_mfma_f32_16x16x32_bf16 v[44:47], v[142:145], v[138:141], v[44:47]
	v_mfma_f32_16x16x32_bf16 v[48:51], v[146:149], v[138:141], v[48:51]
	v_mfma_f32_16x16x32_bf16 v[52:55], v[150:153], v[138:141], v[52:55]
	v_mfma_f32_16x16x32_bf16 v[14:17], v[154:157], v[138:141], v[14:17]
	s_waitcnt lgkmcnt(0)
	s_barrier
; template <class Epi>
; DEV void gemm_tile(const bf16_t* __restrict__ A, int lda, const bf16_t* __restrict__ Bt, int ldb, int K, int tm, int tn, char* smem, const Epi& epi) {
;     ...
;     float* Ct = (float*)smem;
; #pragma unroll
;     for (int m = 0; m < 4; ++m)
; #pragma unroll
;         for (int n = 0; n < 4; ++n) *(f32x4*)(Ct + (wr * 64 + m * 16 + fr) * CP + wc * 64 + n * 16 + fq * 4) = acc[m][n];
;     __syncthreads();
	v_mfma_f32_16x16x32_bf16 v[62:65], v[176:179], v[158:161], v[62:65]
	v_mfma_f32_16x16x32_bf16 v[66:69], v[180:183], v[158:161], v[66:69]
	v_mfma_f32_16x16x32_bf16 v[70:73], v[192:195], v[158:161], v[70:73]
	v_mfma_f32_16x16x32_bf16 v[2:5], v[210:213], v[158:161], v[2:5]
	v_mfma_f32_16x16x32_bf16 v[18:21], v[176:179], v[164:167], v[18:21]
	v_mfma_f32_16x16x32_bf16 v[28:31], v[180:183], v[164:167], v[28:31]
	v_mfma_f32_16x16x32_bf16 v[56:59], v[192:195], v[164:167], v[56:59]
	v_mfma_f32_16x16x32_bf16 v[10:13], v[210:213], v[164:167], v[10:13]
	v_mfma_f32_16x16x32_bf16 v[22:25], v[176:179], v[168:171], v[22:25]
	v_mfma_f32_16x16x32_bf16 v[32:35], v[180:183], v[168:171], v[32:35]
	v_mfma_f32_16x16x32_bf16 v[74:77], v[192:195], v[168:171], v[74:77]
	v_mfma_f32_16x16x32_bf16 v[36:39], v[210:213], v[168:171], v[36:39]
	v_mfma_f32_16x16x32_bf16 v[44:47], v[176:179], v[172:175], v[44:47]
	v_mfma_f32_16x16x32_bf16 v[48:51], v[180:183], v[172:175], v[48:51]
	v_mfma_f32_16x16x32_bf16 v[52:55], v[192:195], v[172:175], v[52:55]
	v_mfma_f32_16x16x32_bf16 v[14:17], v[210:213], v[172:175], v[14:17]
	s_setprio 0
	v_readlane_b32 s88, v255, 24
	v_readlane_b32 s89, v255, 25
	v_readlane_b32 s90, v255, 26
	v_readlane_b32 s91, v255, 27
	v_readlane_b32 s92, v255, 28
	v_readlane_b32 s93, v255, 29
	v_readlane_b32 s94, v255, 30
	v_readlane_b32 s95, v255, 31
	s_nop 7
	s_nop 1
	s_mul_hi_u32 s43, s43, 0x38e38e39
	s_lshr_b32 s94, s43, 2
	s_mul_i32 s43, s94, 0xfffff700
	s_add_i32 s48, s43, s42
	s_cmpk_lt_i32 s48, 0x800
	s_cselect_b64 s[42:43], -1, 0
	s_mul_i32 s45, s94, 0x6000
	s_and_b64 s[46:47], s[42:43], exec
	v_lshl_or_b32 v7, v8, 6, v7
	s_cselect_b32 s45, s45, 0xc0000
	v_lshl_add_u32 v6, v6, 8, 16
	v_lshlrev_b32_e32 v0, 4, v0
	v_mul_lo_u32 v7, v7, s58
	s_add_u32 s45, s10, s45
	v_add3_u32 v0, v6, v0, v7
	v_mov_b32_e32 v6, v163
	s_addc_u32 s46, s11, 0
	s_lshl_b32 s47, s44, 2
	s_waitcnt vmcnt(0)
	s_barrier
	ds_write_b128 v0, v[62:65]
	ds_write_b128 v0, v[66:69] offset:64
	ds_write_b128 v0, v[70:73] offset:128
	ds_write_b128 v0, v[2:5] offset:192
	ds_write_b128 v0, v[18:21] offset:8448
	ds_write_b128 v0, v[28:31] offset:8512
	ds_write_b128 v0, v[56:59] offset:8576
	ds_write_b128 v0, v[10:13] offset:8640
	ds_write_b128 v0, v[22:25] offset:16896
	ds_write_b128 v0, v[32:35] offset:16960
	ds_write_b128 v0, v[74:77] offset:17024
	ds_write_b128 v0, v[36:39] offset:17088
	ds_write_b128 v0, v[44:47] offset:25344
	ds_write_b128 v0, v[48:51] offset:25408
	ds_write_b128 v0, v[52:55] offset:25472
	ds_write_b128 v0, v[14:17] offset:25536
	s_waitcnt lgkmcnt(0)
	s_barrier
	s_add_u32 s44, s45, s47
	v_lshlrev_b32_e32 v0, 4, v6
	s_addc_u32 s45, s46, 0
	v_and_b32_e32 v0, 0x1f0, v0
	v_lshl_add_u64 v[2:3], s[44:45], 0, v[0:1]
	s_movk_i32 s44, 0x2000
	s_add_i32 s46, s48, 0xfffff800
	s_ashr_i32 s49, s48, 31
	v_add_co_u32_e32 v2, vcc, s44, v2
	s_and_b64 s[44:45], s[42:43], exec
	v_readlane_b32 s64, v251, 1
	v_readlane_b32 s67, v251, 4
	v_readlane_b32 s44, v251, 36
	s_cselect_b32 s50, 23, 20
	v_readlane_b32 s66, v251, 3
	s_cselect_b32 s51, s67, s44
	v_readlane_b32 s44, v251, 35
	s_cselect_b32 s52, s66, s44
	s_cselect_b32 s45, s49, 0
	s_cselect_b32 s44, s48, s46
	s_lshl_b32 s46, s94, s50
	s_add_u32 s46, s52, s46
	s_addc_u32 s48, s51, 0
	s_lshl_b64 s[44:45], s[44:45], 12
	s_add_u32 s49, s46, s44
	s_addc_u32 s51, s48, s45
	s_and_b64 s[42:43], s[42:43], exec
	s_cselect_b32 s52, s69, s73
	s_cselect_b32 s53, s68, s72
	s_lshl_b64 s[42:43], s[94:95], s50
	s_add_u32 s50, s53, s42
	s_addc_u32 s52, s52, s43
	s_and_b64 s[42:43], s[6:7], exec
	s_cselect_b32 s43, s46, s50
	s_cselect_b32 s42, s48, s52
	s_add_u32 s44, s43, s44
	s_addc_u32 s45, s42, s45
	s_add_u32 s42, s49, s47
	s_addc_u32 s43, s51, 0
	v_lshl_add_u64 v[14:15], s[42:43], 0, v[0:1]
	v_ashrrev_i32_e32 v48, 5, v6
	s_add_u32 s42, s44, s47
	s_addc_u32 s43, s45, 0
	v_ashrrev_i32_e32 v49, 31, v48
	v_lshl_add_u64 v[16:17], s[42:43], 0, v[0:1]
	v_lshlrev_b64 v[18:19], 12, v[48:49]
	v_addc_co_u32_e32 v3, vcc, 0, v3, vcc
	v_lshl_add_u64 v[6:7], v[16:17], 0, v[18:19]
	global_load_dwordx4 v[2:5], v[2:3], off
	s_mov_b64 s[42:43], 0x8000
	global_load_dwordx4 v[24:27], v[6:7], off
	v_lshl_add_u64 v[52:53], v[18:19], 0, s[42:43]
	v_lshl_add_u64 v[6:7], v[16:17], 0, v[52:53]
	global_load_dwordx4 v[28:31], v[6:7], off
	v_lshl_add_u64 v[54:55], v[18:19], 0, s[90:91]
	v_lshl_add_u64 v[6:7], v[16:17], 0, v[54:55]
	global_load_dwordx4 v[32:35], v[6:7], off
	s_mov_b64 s[42:43], 0x18000
	v_lshl_add_u64 v[56:57], v[18:19], 0, s[42:43]
	v_lshl_add_u64 v[6:7], v[16:17], 0, v[56:57]
	global_load_dwordx4 v[36:39], v[6:7], off
	v_lshl_add_u64 v[58:59], v[18:19], 0, s[92:93]
	v_lshl_add_u64 v[6:7], v[16:17], 0, v[58:59]
	global_load_dwordx4 v[40:43], v[6:7], off
	s_mov_b64 s[42:43], 0x28000
	v_lshl_add_u64 v[60:61], v[18:19], 0, s[42:43]
	v_lshl_add_u64 v[6:7], v[16:17], 0, v[60:61]
	global_load_dwordx4 v[44:47], v[6:7], off
	v_lshl_add_u64 v[22:23], v[18:19], 0, s[0:1]
	v_lshl_add_u64 v[6:7], v[16:17], 0, v[22:23]
	global_load_dwordx4 v[10:13], v[6:7], off
	s_mov_b64 s[0:1], 0x38000
	v_lshl_add_u64 v[20:21], v[18:19], 0, s[0:1]
	v_lshl_add_u64 v[6:7], v[16:17], 0, v[20:21]
	global_load_dwordx4 v[6:9], v[6:7], off
	v_mul_lo_u32 v48, v48, s58
	v_add3_u32 v0, 16, v0, v48
	ds_read_b128 v[48:51], v0
	v_lshl_add_u64 v[22:23], v[14:15], 0, v[22:23]
	s_mov_b64 s[0:1], 0x40000
	s_mov_b64 s[42:43], 0x48000
	v_readlane_b32 s65, v251, 2
	s_waitcnt vmcnt(7) lgkmcnt(0)
;     DEV void operator()(int tm, int tn, const float* Ct) const {
;     ...
; #pragma unroll
;         for (int it0 = 0; it0 < 16; it0 += 8) {
;             f32x4 xv[8];
; #pragma unroll
;             for (int u = 0; u < 8; ++u) xv[u] = *(const f32x4*)(xs + (size_t)(rb + 8 * (it0 + u)) * D);
; #pragma unroll
;             for (int u = 0; u < 8; ++u) { const int r = rb + 8 * (it0 + u); *(f32x4*)(x0 + (size_t)r * D) = xv[u] + g * *(const f32x4*)(Ct + r * CP + c); }
;         }
	v_pk_fma_f32 v[26:27], v[4:5], v[50:51], v[26:27]
	v_pk_fma_f32 v[24:25], v[2:3], v[48:49], v[24:25]
	v_lshl_add_u64 v[48:49], v[14:15], 0, v[18:19]
	global_store_dwordx4 v[48:49], v[24:27], off
	ds_read_b128 v[24:27], v0 offset:4224
	v_lshl_add_u64 v[50:51], v[18:19], 0, s[0:1]
	s_mov_b64 s[0:1], 0x50000
	s_waitcnt vmcnt(7) lgkmcnt(0)
	v_pk_fma_f32 v[26:27], v[4:5], v[26:27], v[30:31]
	v_pk_fma_f32 v[24:25], v[2:3], v[24:25], v[28:29]
	v_lshl_add_u64 v[28:29], v[14:15], 0, v[52:53]
	global_store_dwordx4 v[28:29], v[24:27], off
	ds_read_b128 v[24:27], v0 offset:8448
	v_lshl_add_u64 v[28:29], v[14:15], 0, v[54:55]
	v_lshl_add_u64 v[52:53], v[18:19], 0, s[42:43]
	v_lshl_add_u64 v[54:55], v[18:19], 0, s[0:1]
	s_mov_b64 s[0:1], 0x58000
	s_waitcnt vmcnt(7) lgkmcnt(0)
	v_pk_fma_f32 v[26:27], v[4:5], v[26:27], v[34:35]
	v_pk_fma_f32 v[24:25], v[2:3], v[24:25], v[32:33]
	global_store_dwordx4 v[28:29], v[24:27], off
	ds_read_b128 v[24:27], v0 offset:12672
	v_lshl_add_u64 v[28:29], v[14:15], 0, v[56:57]
	v_lshl_add_u64 v[56:57], v[18:19], 0, s[0:1]
	s_mov_b64 s[0:1], 0x60000
	s_waitcnt vmcnt(7) lgkmcnt(0)
	v_pk_fma_f32 v[26:27], v[4:5], v[26:27], v[38:39]
	v_pk_fma_f32 v[24:25], v[2:3], v[24:25], v[36:37]
	global_store_dwordx4 v[28:29], v[24:27], off
	ds_read_b128 v[24:27], v0 offset:16896
	v_lshl_add_u64 v[28:29], v[14:15], 0, v[58:59]
	v_lshl_add_u64 v[58:59], v[18:19], 0, s[0:1]
	s_mov_b64 s[0:1], 0x68000
	s_waitcnt vmcnt(7) lgkmcnt(0)
	v_pk_fma_f32 v[26:27], v[4:5], v[26:27], v[42:43]
	v_pk_fma_f32 v[24:25], v[2:3], v[24:25], v[40:41]
	global_store_dwordx4 v[28:29], v[24:27], off
	ds_read_b128 v[24:27], v0 offset:21120
	v_lshl_add_u64 v[28:29], v[14:15], 0, v[60:61]
	v_lshl_add_u64 v[60:61], v[18:19], 0, s[0:1]
	s_mov_b64 s[0:1], 0x70000
	s_waitcnt vmcnt(7) lgkmcnt(0)
	v_pk_fma_f32 v[26:27], v[4:5], v[26:27], v[46:47]
	v_pk_fma_f32 v[24:25], v[2:3], v[24:25], v[44:45]
	global_store_dwordx4 v[28:29], v[24:27], off
	ds_read_b128 v[24:27], v0 offset:25344
	ds_read_b128 v[46:49], v0 offset:33792
	s_waitcnt vmcnt(7) lgkmcnt(1)
	v_pk_fma_f32 v[12:13], v[4:5], v[26:27], v[12:13]
	v_pk_fma_f32 v[10:11], v[2:3], v[24:25], v[10:11]
	global_store_dwordx4 v[22:23], v[10:13], off
	ds_read_b128 v[10:13], v0 offset:29568
	s_waitcnt vmcnt(7) lgkmcnt(0)
	v_pk_fma_f32 v[8:9], v[4:5], v[12:13], v[8:9]
	v_pk_fma_f32 v[6:7], v[2:3], v[10:11], v[6:7]
	v_lshl_add_u64 v[10:11], v[14:15], 0, v[20:21]
	global_store_dwordx4 v[10:11], v[6:9], off
	v_lshl_add_u64 v[20:21], v[18:19], 0, s[0:1]
	s_mov_b64 s[0:1], 0x78000
	v_lshl_add_u64 v[6:7], v[16:17], 0, v[50:51]
	global_load_dwordx4 v[22:25], v[6:7], off
	v_lshl_add_u64 v[6:7], v[16:17], 0, v[52:53]
	global_load_dwordx4 v[26:29], v[6:7], off
	v_lshl_add_u64 v[6:7], v[16:17], 0, v[54:55]
	global_load_dwordx4 v[30:33], v[6:7], off
	v_lshl_add_u64 v[6:7], v[16:17], 0, v[56:57]
	global_load_dwordx4 v[34:37], v[6:7], off
	v_lshl_add_u64 v[6:7], v[16:17], 0, v[58:59]
	global_load_dwordx4 v[38:41], v[6:7], off
	v_lshl_add_u64 v[6:7], v[16:17], 0, v[60:61]
	global_load_dwordx4 v[42:45], v[6:7], off
	v_lshl_add_u64 v[6:7], v[16:17], 0, v[20:21]
	global_load_dwordx4 v[10:13], v[6:7], off
	v_lshl_add_u64 v[18:19], v[18:19], 0, s[0:1]
	v_lshl_add_u64 v[6:7], v[16:17], 0, v[18:19]
	global_load_dwordx4 v[6:9], v[6:7], off
	v_lshl_add_u64 v[16:17], v[14:15], 0, v[50:51]
	s_waitcnt vmcnt(7)
	v_pk_fma_f32 v[24:25], v[4:5], v[48:49], v[24:25]
	v_pk_fma_f32 v[22:23], v[2:3], v[46:47], v[22:23]
	global_store_dwordx4 v[16:17], v[22:25], off
	ds_read_b128 v[22:25], v0 offset:38016
	v_lshl_add_u64 v[16:17], v[14:15], 0, v[52:53]
	s_waitcnt vmcnt(7) lgkmcnt(0)
	v_pk_fma_f32 v[24:25], v[4:5], v[24:25], v[28:29]
	v_pk_fma_f32 v[22:23], v[2:3], v[22:23], v[26:27]
	global_store_dwordx4 v[16:17], v[22:25], off
	ds_read_b128 v[22:25], v0 offset:42240
	v_lshl_add_u64 v[16:17], v[14:15], 0, v[54:55]
	s_waitcnt vmcnt(7) lgkmcnt(0)
	v_pk_fma_f32 v[24:25], v[4:5], v[24:25], v[32:33]
	v_pk_fma_f32 v[22:23], v[2:3], v[22:23], v[30:31]
	global_store_dwordx4 v[16:17], v[22:25], off
	ds_read_b128 v[22:25], v0 offset:46464
	v_lshl_add_u64 v[16:17], v[14:15], 0, v[56:57]
	s_waitcnt vmcnt(7) lgkmcnt(0)
	v_pk_fma_f32 v[24:25], v[4:5], v[24:25], v[36:37]
	v_pk_fma_f32 v[22:23], v[2:3], v[22:23], v[34:35]
	global_store_dwordx4 v[16:17], v[22:25], off
	ds_read_b128 v[22:25], v0 offset:50688
	v_lshl_add_u64 v[16:17], v[14:15], 0, v[58:59]
	s_waitcnt vmcnt(7) lgkmcnt(0)
	v_pk_fma_f32 v[24:25], v[4:5], v[24:25], v[40:41]
	v_pk_fma_f32 v[22:23], v[2:3], v[22:23], v[38:39]
	global_store_dwordx4 v[16:17], v[22:25], off
	ds_read_b128 v[22:25], v0 offset:54912
	v_lshl_add_u64 v[16:17], v[14:15], 0, v[60:61]
	s_waitcnt vmcnt(7) lgkmcnt(0)
	v_pk_fma_f32 v[24:25], v[4:5], v[24:25], v[44:45]
	v_pk_fma_f32 v[22:23], v[2:3], v[22:23], v[42:43]
	global_store_dwordx4 v[16:17], v[22:25], off
	ds_read_b128 v[22:25], v0 offset:59136
	v_lshl_add_u64 v[16:17], v[14:15], 0, v[20:21]
	s_waitcnt vmcnt(7) lgkmcnt(0)
	v_pk_fma_f32 v[12:13], v[4:5], v[24:25], v[12:13]
	v_pk_fma_f32 v[10:11], v[2:3], v[22:23], v[10:11]
	global_store_dwordx4 v[16:17], v[10:13], off
	ds_read_b128 v[10:13], v0 offset:63360
	s_waitcnt vmcnt(7) lgkmcnt(0)
	v_pk_fma_f32 v[4:5], v[4:5], v[12:13], v[8:9]
	v_pk_fma_f32 v[2:3], v[2:3], v[10:11], v[6:7]
	v_lshl_add_u64 v[6:7], v[14:15], 0, v[18:19]
	global_store_dwordx4 v[6:7], v[2:5], off
	s_barrier
	s_branch .LBB0_161

; DEV int tid_() { int t = __builtin_amdgcn_workitem_id_x(); asm volatile("" : "+v"(t)); return t; }
; template <class Epi>
; DEV void gemm_tile(const bf16_t* __restrict__ A, int lda, const bf16_t* __restrict__ Bt, int ldb, int K, int tm, int tn, char* smem, const Epi& epi) {
;     const int tid = tid_(), lane = tid & 63, wid = tid >> 6, wr = wid >> 1, wc = wid & 1, fr = lane & 15, fq = lane >> 4;
;     bf16_t* As = (bf16_t*)smem;
;     bf16_t* Bs = As + 2 * 128 * 64;
;     const int lrow = tid >> 3, lcc = (tid & 7) * 8, lsw = (((tid & 7) ^ (lrow & 7)) * 8);
;     const bf16_t* Ag = A + (size_t)(tm * 128 + lrow) * lda + lcc;
;     const bf16_t* Bg = Bt + (size_t)(tn * 128 + lrow) * ldb + lcc;
;     f32x4 acc[4][4];
; #pragma unroll
;     for (int m = 0; m < 4; ++m)
; #pragma unroll
;         for (int n = 0; n < 4; ++n) acc[m][n] = (f32x4){0.f, 0.f, 0.f, 0.f};
;     const int gsw = (((tid & 7) ^ (lrow & 7)) * 8);
;     const bf16_t* Ad = A + (size_t)(tm * 128 + lrow) * lda + gsw;
;     const bf16_t* Bd = Bt + (size_t)(tn * 128 + lrow) * ldb + gsw;
;     char* Asb = (char*)As; char* Bsb = (char*)Bs;
;     ...
;     const int nk = K >> 6;
;     G_DMA(0, 0);
;     asm volatile("s_waitcnt vmcnt(0)" ::: "memory");
;     __syncthreads();
; #pragma unroll 4
;     for (int kt = 0; kt < nk; ++kt) {
;         const int cur = kt & 1;
;         if (kt + 1 < nk) G_DMA(cur ^ 1, kt + 1);
.LBB0_179:
	s_lshr_b32 s39, s37, 3
	v_readlane_b32 s38, v253, 31
	s_add_i32 s39, s39, s38
	s_lshl_b32 s38, s39, 7
	s_mul_hi_u32 s42, s38, 0x38e38e39
	s_lshr_b32 s42, s42, 9
	s_mulk_i32 s42, 0x900
	s_sub_i32 s42, s38, s42
	s_cmpk_gt_u32 s42, 0x7ff
	s_cselect_b64 s[42:43], -1, 0
	s_and_b64 s[42:43], s[54:55], s[42:43]
	s_and_b64 vcc, exec, s[42:43]
	s_cbranch_vccnz .LBB0_178
	v_mov_b32_e32 v10, v163
	s_and_b32 s42, s36, 0x380
	s_waitcnt vmcnt(10)
	v_ashrrev_i32_e32 v0, 3, v10
	v_readlane_b32 s44, v251, 27
	v_add_u32_e32 v4, s38, v0
	v_add_u32_e32 v8, s42, v0
	v_xor_b32_e32 v0, v0, v10
	v_readlane_b32 s45, v251, 28
	v_lshlrev_b32_e32 v0, 4, v0
	v_lshl_add_u32 v14, v10, 4, 16
	v_mov_b64_e32 v[2:3], s[44:45]
	v_mad_i64_i32 v[2:3], s[44:45], v4, s29, v[2:3]
	v_mov_b64_e32 v[4:5], s[0:1]
	v_and_b32_e32 v0, 0x70, v0
	v_add_u32_e32 v13, 0x8000, v14
	v_readfirstlane_b32 s63, v14
	v_mad_i64_i32 v[8:9], s[44:45], v8, s29, v[4:5]
	v_lshl_add_u64 v[4:5], v[2:3], 0, v[0:1]
	s_mov_b32 m0, s63
	v_readfirstlane_b32 s51, v13
	v_add_u32_e32 v15, 0x1000, v14
	v_lshl_add_u64 v[2:3], v[8:9], 0, v[0:1]
	global_load_lds_dwordx4 v[4:5], off
	s_mov_b32 m0, s51
	s_mov_b64 s[44:45], 0x2c000
	v_readfirstlane_b32 s52, v15
	v_add_u32_e32 v16, 0x9000, v14
	global_load_lds_dwordx4 v[2:3], off
	v_lshl_add_u64 v[8:9], v[4:5], 0, s[44:45]
	s_mov_b32 m0, s52
	v_readfirstlane_b32 s53, v16
	v_add_u32_e32 v17, 0x2000, v14
	global_load_lds_dwordx4 v[8:9], off
	v_lshl_add_u64 v[8:9], v[2:3], 0, s[44:45]
	s_mov_b32 m0, s53
	s_mov_b64 s[44:45], 0x58000
	v_readfirstlane_b32 s62, v17
	s_waitcnt vmcnt(0)
	v_add_u32_e32 v18, 0xa000, v14
	global_load_lds_dwordx4 v[8:9], off
	v_lshl_add_u64 v[8:9], v[4:5], 0, s[44:45]
	s_mov_b32 m0, s62
	v_readfirstlane_b32 s64, v18
	v_add_u32_e32 v19, 0x3000, v14
	global_load_lds_dwordx4 v[8:9], off
	v_lshl_add_u64 v[8:9], v[2:3], 0, s[44:45]
	s_mov_b32 m0, s64
	s_mov_b64 s[44:45], 0x84000
	v_readfirstlane_b32 s65, v19
	v_add_u32_e32 v20, 0xb000, v14
	global_load_lds_dwordx4 v[8:9], off
	v_lshl_add_u64 v[8:9], v[4:5], 0, s[44:45]
	s_mov_b32 m0, s65
	v_readfirstlane_b32 s84, v20
	global_load_lds_dwordx4 v[8:9], off
	v_lshl_add_u64 v[8:9], v[2:3], 0, s[44:45]
	s_mov_b32 m0, s84
	v_and_b32_e32 v7, 15, v10
	global_load_lds_dwordx4 v[8:9], off
	v_ashrrev_i32_e32 v8, 7, v10
	v_bfe_u32 v6, v10, 6, 1
	v_lshlrev_b32_e32 v9, 13, v8
	v_lshlrev_b32_e32 v12, 7, v7
	v_add_u32_e32 v21, 0x4000, v14
	v_lshrrev_b32_e32 v11, 4, v10
	v_bfe_u32 v0, v10, 4, 2
	v_add3_u32 v29, 16, v9, v12
	v_and_b32_e32 v9, 7, v10
	v_lshlrev_b32_e32 v10, 13, v6
	s_mov_b64 s[44:45], 0x80
	v_add_u32_e32 v22, 0xc000, v14
	v_readfirstlane_b32 s47, v21
	v_bitop3_b32 v30, v11, v9, 3 bitop3:0x6c
	v_add3_u32 v12, 16, v10, v12
	v_lshl_add_u64 v[10:11], v[4:5], 0, s[44:45]
	s_mov_b32 m0, s47
	v_readfirstlane_b32 s43, v22
	s_waitcnt vmcnt(0)
	s_waitcnt vmcnt(0) lgkmcnt(0)
	s_barrier
	v_writelane_b32 v255, s88, 24
	v_writelane_b32 v255, s89, 25
	v_writelane_b32 v255, s90, 26
	v_writelane_b32 v255, s91, 27
	v_writelane_b32 v255, s92, 28
	v_writelane_b32 v255, s93, 29
	v_writelane_b32 v255, s94, 30
	v_writelane_b32 v255, s95, 31
	v_readfirstlane_b32 s88, v4
	v_readfirstlane_b32 s89, v5
	v_readfirstlane_b32 s90, v2
	v_readfirstlane_b32 s91, v3
	v_lshl_add_u32 v242, v163, 4, 16
	s_and_b32 s88, s88, 0xffffff80
	s_and_b32 s90, s90, 0xffffff80
	v_readfirstlane_b32 s93, v242
	v_subrev_u32_e32 v250, s88, v4
	v_subrev_u32_e32 v246, s90, v2
	v_add_u32_e32 v249, 0x2c000, v250
	v_add_u32_e32 v245, 0x2c000, v246
	v_add_u32_e32 v248, 0x58000, v250
	v_add_u32_e32 v244, 0x58000, v246
	v_add_u32_e32 v247, 0x84000, v250
	v_add_u32_e32 v243, 0x84000, v246
	s_add_u32 s94, s93, 0x4000
	s_add_u32 s88, s88, 0x80
	s_addc_u32 s89, s89, 0
	s_add_u32 s90, s90, 0x80
	s_addc_u32 s91, s91, 0
	v_and_b32_e32 v242, 15, v163
	v_lshlrev_b32_e32 v242, 7, v242
	v_bfe_u32 v217, v163, 4, 2
	v_and_b32_e32 v218, 7, v163
	v_xor_b32_e32 v217, v217, v218
	v_lshlrev_b32_e32 v218, 4, v217
	v_xor_b32_e32 v217, 4, v217
	v_lshlrev_b32_e32 v217, 4, v217
	v_lshrrev_b32_e32 v184, 7, v163
	v_lshl_add_u32 v184, v184, 13, v242
	v_add_u32_e32 v184, 16, v184
	v_bfe_u32 v215, v163, 6, 1
	v_lshl_add_u32 v215, v215, 13, v242
	v_add_u32_e32 v215, 16, v215
	v_add_u32_e32 v214, v184, v217
	v_add_u32_e32 v216, v215, v217
	v_add_u32_e32 v184, v184, v218
	v_add_u32_e32 v215, v215, v218
	v_mov_b32_e32 v62, 0
	v_mov_b32_e32 v63, 0
	v_mov_b32_e32 v64, 0
	v_mov_b32_e32 v65, 0
	v_mov_b32_e32 v66, 0
	v_mov_b32_e32 v67, 0
	v_mov_b32_e32 v68, 0
	v_mov_b32_e32 v69, 0
	v_mov_b32_e32 v70, 0
	v_mov_b32_e32 v71, 0
	v_mov_b32_e32 v72, 0
	v_mov_b32_e32 v73, 0
	v_mov_b32_e32 v2, 0
	v_mov_b32_e32 v3, 0
	v_mov_b32_e32 v4, 0
	v_mov_b32_e32 v5, 0
	v_mov_b32_e32 v14, 0
	v_mov_b32_e32 v15, 0
	v_mov_b32_e32 v16, 0
	v_mov_b32_e32 v17, 0
	v_mov_b32_e32 v22, 0
	v_mov_b32_e32 v23, 0
	v_mov_b32_e32 v24, 0
	v_mov_b32_e32 v25, 0
	v_mov_b32_e32 v30, 0
	v_mov_b32_e32 v31, 0
	v_mov_b32_e32 v32, 0
	v_mov_b32_e32 v33, 0
	v_mov_b32_e32 v18, 0
	v_mov_b32_e32 v19, 0
	v_mov_b32_e32 v20, 0
	v_mov_b32_e32 v21, 0
	v_mov_b32_e32 v26, 0
	v_mov_b32_e32 v27, 0
	v_mov_b32_e32 v28, 0
	v_mov_b32_e32 v29, 0
	v_mov_b32_e32 v34, 0
	v_mov_b32_e32 v35, 0
	v_mov_b32_e32 v36, 0
	v_mov_b32_e32 v37, 0
	v_mov_b32_e32 v58, 0
	v_mov_b32_e32 v59, 0
	v_mov_b32_e32 v60, 0
	v_mov_b32_e32 v61, 0
	v_mov_b32_e32 v38, 0
	v_mov_b32_e32 v39, 0
	v_mov_b32_e32 v40, 0
	v_mov_b32_e32 v41, 0
	v_mov_b32_e32 v46, 0
	v_mov_b32_e32 v47, 0
	v_mov_b32_e32 v48, 0
	v_mov_b32_e32 v49, 0
	v_mov_b32_e32 v50, 0
	v_mov_b32_e32 v51, 0
	v_mov_b32_e32 v52, 0
	v_mov_b32_e32 v53, 0
	v_mov_b32_e32 v54, 0
	v_mov_b32_e32 v55, 0
	v_mov_b32_e32 v56, 0
	v_mov_b32_e32 v57, 0
	v_mov_b32_e32 v10, 0
	v_mov_b32_e32 v11, 0
	v_mov_b32_e32 v12, 0
	v_mov_b32_e32 v13, 0
	s_mov_b32 m0, s94
	s_nop 0
	global_load_lds_dwordx4 v250, s[88:89]
	s_add_u32 m0, m0, 0x1000
	s_nop 0
	global_load_lds_dwordx4 v249, s[88:89]
	s_add_u32 m0, m0, 0x1000
	s_nop 0
	global_load_lds_dwordx4 v248, s[88:89]
	s_add_u32 m0, m0, 0x1000
	s_nop 0
	global_load_lds_dwordx4 v247, s[88:89]
	s_add_u32 m0, m0, 0x5000
	s_nop 0
	global_load_lds_dwordx4 v246, s[90:91]
	s_add_u32 m0, m0, 0x1000
	s_nop 0
	global_load_lds_dwordx4 v245, s[90:91]
	s_add_u32 m0, m0, 0x1000
	s_nop 0
	global_load_lds_dwordx4 v244, s[90:91]
	s_add_u32 m0, m0, 0x1000
	s_nop 0
	global_load_lds_dwordx4 v243, s[90:91]
	s_add_u32 s88, s88, 0x80
	s_addc_u32 s89, s89, 0
	s_add_u32 s90, s90, 0x80
	s_addc_u32 s91, s91, 0
	ds_read_b128 v[126:129], v184
	ds_read_b128 v[130:133], v184 offset:2048
	ds_read_b128 v[134:137], v184 offset:4096
	ds_read_b128 v[138:141], v184 offset:6144
	ds_read_b128 v[142:145], v215 offset:32768
	ds_read_b128 v[146:149], v215 offset:34816
	ds_read_b128 v[150:153], v215 offset:36864
	ds_read_b128 v[154:157], v215 offset:38912
	v_readlane_b32 s95, v251, 0
	s_nop 0
	s_cmp_lt_u32 s95, 0x100
	s_setprio 1
	s_cbranch_scc1 .Lgemm_down_lowprio
	s_setprio 2

; #define G_MMA(ks_) __builtin_amdgcn_s_setprio(1); _Pragma("unroll") for (int m = 0; m < 4; ++m) \
;         _Pragma("unroll") for (int n = 0; n < 4; ++n) acc[m][n] = __builtin_amdgcn_mfma_f32_16x16x32_bf16(bfv##ks_[n], af##ks_[m], acc[m][n], 0, 0, 0); __builtin_amdgcn_s_setprio(0);
; template <class Epi>
; DEV void gemm_tile(const bf16_t* __restrict__ A, int lda, const bf16_t* __restrict__ Bt, int ldb, int K, int tm, int tn, char* smem, const Epi& epi) {
;     ...
;     for (int kt = 0; kt < nk; ++kt) {
;         const int cur = kt & 1;
;         if (kt + 1 < nk) G_DMA(cur ^ 1, kt + 1);
;         {
;             G_FRAGS(cur, 0)
;             G_MMA(0)
;             G_FRAGS(cur, 1)
;             G_MMA(1)
;         }
;         asm volatile("s_waitcnt vmcnt(0)" ::: "memory");
;         __syncthreads();
.Lgemm_down_loop:
	ds_read_b128 v[158:161], v214
	ds_read_b128 v[164:167], v214 offset:2048
	ds_read_b128 v[168:171], v214 offset:4096
	ds_read_b128 v[172:175], v214 offset:6144
	ds_read_b128 v[176:179], v216 offset:32768
	ds_read_b128 v[180:183], v216 offset:34816
	ds_read_b128 v[192:195], v216 offset:36864
	ds_read_b128 v[210:213], v216 offset:38912
	s_waitcnt lgkmcnt(8)
	v_mfma_f32_16x16x32_bf16 v[62:65], v[142:145], v[126:129], v[62:65]
	v_mfma_f32_16x16x32_bf16 v[66:69], v[146:149], v[126:129], v[66:69]
	v_mfma_f32_16x16x32_bf16 v[70:73], v[150:153], v[126:129], v[70:73]
	v_mfma_f32_16x16x32_bf16 v[2:5], v[154:157], v[126:129], v[2:5]
	v_mfma_f32_16x16x32_bf16 v[14:17], v[142:145], v[130:133], v[14:17]
	v_mfma_f32_16x16x32_bf16 v[22:25], v[146:149], v[130:133], v[22:25]
	v_mfma_f32_16x16x32_bf16 v[30:33], v[150:153], v[130:133], v[30:33]
	v_mfma_f32_16x16x32_bf16 v[18:21], v[154:157], v[130:133], v[18:21]
	v_mfma_f32_16x16x32_bf16 v[26:29], v[142:145], v[134:137], v[26:29]
	v_mfma_f32_16x16x32_bf16 v[34:37], v[146:149], v[134:137], v[34:37]
	v_mfma_f32_16x16x32_bf16 v[58:61], v[150:153], v[134:137], v[58:61]
	v_mfma_f32_16x16x32_bf16 v[38:41], v[154:157], v[134:137], v[38:41]
	v_mfma_f32_16x16x32_bf16 v[46:49], v[142:145], v[138:141], v[46:49]
	v_mfma_f32_16x16x32_bf16 v[50:53], v[146:149], v[138:141], v[50:53]
	v_mfma_f32_16x16x32_bf16 v[54:57], v[150:153], v[138:141], v[54:57]
	v_mfma_f32_16x16x32_bf16 v[10:13], v[154:157], v[138:141], v[10:13]
	s_waitcnt vmcnt(0) lgkmcnt(0)
	s_barrier
	ds_read_b128 v[126:129], v184 offset:16384
	ds_read_b128 v[130:133], v184 offset:18432
	ds_read_b128 v[134:137], v184 offset:20480
	ds_read_b128 v[138:141], v184 offset:22528
	ds_read_b128 v[142:145], v215 offset:49152
	ds_read_b128 v[146:149], v215 offset:51200
	ds_read_b128 v[150:153], v215 offset:53248
	ds_read_b128 v[154:157], v215 offset:55296
	s_mov_b32 m0, s93
	v_mfma_f32_16x16x32_bf16 v[62:65], v[176:179], v[158:161], v[62:65]
	global_load_lds_dwordx4 v250, s[88:89]
	s_add_u32 m0, m0, 0x1000
	v_mfma_f32_16x16x32_bf16 v[66:69], v[180:183], v[158:161], v[66:69]
	global_load_lds_dwordx4 v249, s[88:89]
	s_add_u32 m0, m0, 0x1000
	v_mfma_f32_16x16x32_bf16 v[70:73], v[192:195], v[158:161], v[70:73]
	global_load_lds_dwordx4 v248, s[88:89]
	s_add_u32 m0, m0, 0x1000
	v_mfma_f32_16x16x32_bf16 v[2:5], v[210:213], v[158:161], v[2:5]
	global_load_lds_dwordx4 v247, s[88:89]
	s_add_u32 m0, m0, 0x5000
	v_mfma_f32_16x16x32_bf16 v[14:17], v[176:179], v[164:167], v[14:17]
	global_load_lds_dwordx4 v246, s[90:91]
	s_add_u32 m0, m0, 0x1000
	v_mfma_f32_16x16x32_bf16 v[22:25], v[180:183], v[164:167], v[22:25]
	global_load_lds_dwordx4 v245, s[90:91]
	s_add_u32 m0, m0, 0x1000
	v_mfma_f32_16x16x32_bf16 v[30:33], v[192:195], v[164:167], v[30:33]
	global_load_lds_dwordx4 v244, s[90:91]
	s_add_u32 m0, m0, 0x1000
	v_mfma_f32_16x16x32_bf16 v[18:21], v[210:213], v[164:167], v[18:21]
	global_load_lds_dwordx4 v243, s[90:91]
	v_mfma_f32_16x16x32_bf16 v[26:29], v[176:179], v[168:171], v[26:29]
	s_add_u32 s88, s88, 0x80
	v_mfma_f32_16x16x32_bf16 v[34:37], v[180:183], v[168:171], v[34:37]
	s_addc_u32 s89, s89, 0
	v_mfma_f32_16x16x32_bf16 v[58:61], v[192:195], v[168:171], v[58:61]
	s_add_u32 s90, s90, 0x80
	v_mfma_f32_16x16x32_bf16 v[38:41], v[210:213], v[168:171], v[38:41]
	s_addc_u32 s91, s91, 0
	v_mfma_f32_16x16x32_bf16 v[46:49], v[176:179], v[172:175], v[46:49]
	v_mfma_f32_16x16x32_bf16 v[50:53], v[180:183], v[172:175], v[50:53]
	v_mfma_f32_16x16x32_bf16 v[54:57], v[192:195], v[172:175], v[54:57]
	v_mfma_f32_16x16x32_bf16 v[10:13], v[210:213], v[172:175], v[10:13]
	ds_read_b128 v[158:161], v214 offset:16384
	ds_read_b128 v[164:167], v214 offset:18432
	ds_read_b128 v[168:171], v214 offset:20480
	ds_read_b128 v[172:175], v214 offset:22528
	ds_read_b128 v[176:179], v216 offset:49152
	ds_read_b128 v[180:183], v216 offset:51200
	ds_read_b128 v[192:195], v216 offset:53248
	ds_read_b128 v[210:213], v216 offset:55296
	s_waitcnt lgkmcnt(8)
	v_mfma_f32_16x16x32_bf16 v[62:65], v[142:145], v[126:129], v[62:65]
	v_mfma_f32_16x16x32_bf16 v[66:69], v[146:149], v[126:129], v[66:69]
	v_mfma_f32_16x16x32_bf16 v[70:73], v[150:153], v[126:129], v[70:73]
	v_mfma_f32_16x16x32_bf16 v[2:5], v[154:157], v[126:129], v[2:5]
	v_mfma_f32_16x16x32_bf16 v[14:17], v[142:145], v[130:133], v[14:17]
	v_mfma_f32_16x16x32_bf16 v[22:25], v[146:149], v[130:133], v[22:25]
	v_mfma_f32_16x16x32_bf16 v[30:33], v[150:153], v[130:133], v[30:33]
	v_mfma_f32_16x16x32_bf16 v[18:21], v[154:157], v[130:133], v[18:21]
	v_mfma_f32_16x16x32_bf16 v[26:29], v[142:145], v[134:137], v[26:29]
	v_mfma_f32_16x16x32_bf16 v[34:37], v[146:149], v[134:137], v[34:37]
	v_mfma_f32_16x16x32_bf16 v[58:61], v[150:153], v[134:137], v[58:61]
	v_mfma_f32_16x16x32_bf16 v[38:41], v[154:157], v[134:137], v[38:41]
	v_mfma_f32_16x16x32_bf16 v[46:49], v[142:145], v[138:141], v[46:49]
	v_mfma_f32_16x16x32_bf16 v[50:53], v[146:149], v[138:141], v[50:53]
	v_mfma_f32_16x16x32_bf16 v[54:57], v[150:153], v[138:141], v[54:57]
	v_mfma_f32_16x16x32_bf16 v[10:13], v[154:157], v[138:141], v[10:13]
	s_waitcnt vmcnt(0) lgkmcnt(0)
	s_barrier
; #define G_MMA(ks_) __builtin_amdgcn_s_setprio(1); _Pragma("unroll") for (int m = 0; m < 4; ++m) \
;         _Pragma("unroll") for (int n = 0; n < 4; ++n) acc[m][n] = __builtin_amdgcn_mfma_f32_16x16x32_bf16(bfv##ks_[n], af##ks_[m], acc[m][n], 0, 0, 0); __builtin_amdgcn_s_setprio(0);
; template <class Epi>
; DEV void gemm_tile(const bf16_t* __restrict__ A, int lda, const bf16_t* __restrict__ Bt, int ldb, int K, int tm, int tn, char* smem, const Epi& epi) {
;     ...
;     for (int kt = 0; kt < nk; ++kt) {
;         const int cur = kt & 1;
;         if (kt + 1 < nk) G_DMA(cur ^ 1, kt + 1);
;         {
;             G_FRAGS(cur, 0)
;             G_MMA(0)
;             G_FRAGS(cur, 1)
;             G_MMA(1)
;         }
;         asm volatile("s_waitcnt vmcnt(0)" ::: "memory");
;         __syncthreads();
;     }
	ds_read_b128 v[126:129], v184
	ds_read_b128 v[130:133], v184 offset:2048
	ds_read_b128 v[134:137], v184 offset:4096
	ds_read_b128 v[138:141], v184 offset:6144
	ds_read_b128 v[142:145], v215 offset:32768
	ds_read_b128 v[146:149], v215 offset:34816
	ds_read_b128 v[150:153], v215 offset:36864
	ds_read_b128 v[154:157], v215 offset:38912
	s_mov_b32 m0, s94
	v_mfma_f32_16x16x32_bf16 v[62:65], v[176:179], v[158:161], v[62:65]
	global_load_lds_dwordx4 v250, s[88:89]
	s_add_u32 m0, m0, 0x1000
	v_mfma_f32_16x16x32_bf16 v[66:69], v[180:183], v[158:161], v[66:69]
	global_load_lds_dwordx4 v249, s[88:89]
	s_add_u32 m0, m0, 0x1000
	v_mfma_f32_16x16x32_bf16 v[70:73], v[192:195], v[158:161], v[70:73]
	global_load_lds_dwordx4 v248, s[88:89]
	s_add_u32 m0, m0, 0x1000
	v_mfma_f32_16x16x32_bf16 v[2:5], v[210:213], v[158:161], v[2:5]
	global_load_lds_dwordx4 v247, s[88:89]
	s_add_u32 m0, m0, 0x5000
	v_mfma_f32_16x16x32_bf16 v[14:17], v[176:179], v[164:167], v[14:17]
	global_load_lds_dwordx4 v246, s[90:91]
	s_add_u32 m0, m0, 0x1000
	v_mfma_f32_16x16x32_bf16 v[22:25], v[180:183], v[164:167], v[22:25]
	global_load_lds_dwordx4 v245, s[90:91]
	s_add_u32 m0, m0, 0x1000
	v_mfma_f32_16x16x32_bf16 v[30:33], v[192:195], v[164:167], v[30:33]
	global_load_lds_dwordx4 v244, s[90:91]
	s_add_u32 m0, m0, 0x1000
	v_mfma_f32_16x16x32_bf16 v[18:21], v[210:213], v[164:167], v[18:21]
	global_load_lds_dwordx4 v243, s[90:91]
	v_mfma_f32_16x16x32_bf16 v[26:29], v[176:179], v[168:171], v[26:29]
	s_add_u32 s88, s88, 0x80
	v_mfma_f32_16x16x32_bf16 v[34:37], v[180:183], v[168:171], v[34:37]
	s_addc_u32 s89, s89, 0
	v_mfma_f32_16x16x32_bf16 v[58:61], v[192:195], v[168:171], v[58:61]
	s_add_u32 s90, s90, 0x80
	v_mfma_f32_16x16x32_bf16 v[38:41], v[210:213], v[168:171], v[38:41]
	s_addc_u32 s91, s91, 0
	v_mfma_f32_16x16x32_bf16 v[46:49], v[176:179], v[172:175], v[46:49]
	v_mfma_f32_16x16x32_bf16 v[50:53], v[180:183], v[172:175], v[50:53]
	v_mfma_f32_16x16x32_bf16 v[54:57], v[192:195], v[172:175], v[54:57]
	v_mfma_f32_16x16x32_bf16 v[10:13], v[210:213], v[172:175], v[10:13]
	s_sub_u32 s92, s92, 1
	s_cmp_lg_u32 s92, 0
	s_cbranch_scc1 .Lgemm_down_loop
	ds_read_b128 v[158:161], v214
	ds_read_b128 v[164:167], v214 offset:2048
	ds_read_b128 v[168:171], v214 offset:4096
	ds_read_b128 v[172:175], v214 offset:6144
	ds_read_b128 v[176:179], v216 offset:32768
	ds_read_b128 v[180:183], v216 offset:34816
	ds_read_b128 v[192:195], v216 offset:36864
	ds_read_b128 v[210:213], v216 offset:38912
	s_waitcnt lgkmcnt(8)
	v_mfma_f32_16x16x32_bf16 v[62:65], v[142:145], v[126:129], v[62:65]
	v_mfma_f32_16x16x32_bf16 v[66:69], v[146:149], v[126:129], v[66:69]
	v_mfma_f32_16x16x32_bf16 v[70:73], v[150:153], v[126:129], v[70:73]
	v_mfma_f32_16x16x32_bf16 v[2:5], v[154:157], v[126:129], v[2:5]
	v_mfma_f32_16x16x32_bf16 v[14:17], v[142:145], v[130:133], v[14:17]
	v_mfma_f32_16x16x32_bf16 v[22:25], v[146:149], v[130:133], v[22:25]
	v_mfma_f32_16x16x32_bf16 v[30:33], v[150:153], v[130:133], v[30:33]
	v_mfma_f32_16x16x32_bf16 v[18:21], v[154:157], v[130:133], v[18:21]
	v_mfma_f32_16x16x32_bf16 v[26:29], v[142:145], v[134:137], v[26:29]
	v_mfma_f32_16x16x32_bf16 v[34:37], v[146:149], v[134:137], v[34:37]
	v_mfma_f32_16x16x32_bf16 v[58:61], v[150:153], v[134:137], v[58:61]
	v_mfma_f32_16x16x32_bf16 v[38:41], v[154:157], v[134:137], v[38:41]
	v_mfma_f32_16x16x32_bf16 v[46:49], v[142:145], v[138:141], v[46:49]
	v_mfma_f32_16x16x32_bf16 v[50:53], v[146:149], v[138:141], v[50:53]
	v_mfma_f32_16x16x32_bf16 v[54:57], v[150:153], v[138:141], v[54:57]
	v_mfma_f32_16x16x32_bf16 v[10:13], v[154:157], v[138:141], v[10:13]
	s_waitcnt vmcnt(0) lgkmcnt(0)
	s_barrier
	ds_read_b128 v[126:129], v184 offset:16384
	ds_read_b128 v[130:133], v184 offset:18432
	ds_read_b128 v[134:137], v184 offset:20480
	ds_read_b128 v[138:141], v184 offset:22528
	ds_read_b128 v[142:145], v215 offset:49152
	ds_read_b128 v[146:149], v215 offset:51200
	ds_read_b128 v[150:153], v215 offset:53248
	ds_read_b128 v[154:157], v215 offset:55296
	v_mfma_f32_16x16x32_bf16 v[62:65], v[176:179], v[158:161], v[62:65]
	v_mfma_f32_16x16x32_bf16 v[66:69], v[180:183], v[158:161], v[66:69]
	v_mfma_f32_16x16x32_bf16 v[70:73], v[192:195], v[158:161], v[70:73]
	v_mfma_f32_16x16x32_bf16 v[2:5], v[210:213], v[158:161], v[2:5]
	v_mfma_f32_16x16x32_bf16 v[14:17], v[176:179], v[164:167], v[14:17]
	v_mfma_f32_16x16x32_bf16 v[22:25], v[180:183], v[164:167], v[22:25]
	v_mfma_f32_16x16x32_bf16 v[30:33], v[192:195], v[164:167], v[30:33]
	v_mfma_f32_16x16x32_bf16 v[18:21], v[210:213], v[164:167], v[18:21]
	v_mfma_f32_16x16x32_bf16 v[26:29], v[176:179], v[168:171], v[26:29]
	v_mfma_f32_16x16x32_bf16 v[34:37], v[180:183], v[168:171], v[34:37]
	v_mfma_f32_16x16x32_bf16 v[58:61], v[192:195], v[168:171], v[58:61]
	v_mfma_f32_16x16x32_bf16 v[38:41], v[210:213], v[168:171], v[38:41]
	v_mfma_f32_16x16x32_bf16 v[46:49], v[176:179], v[172:175], v[46:49]
	v_mfma_f32_16x16x32_bf16 v[50:53], v[180:183], v[172:175], v[50:53]
	v_mfma_f32_16x16x32_bf16 v[54:57], v[192:195], v[172:175], v[54:57]
	v_mfma_f32_16x16x32_bf16 v[10:13], v[210:213], v[172:175], v[10:13]
	ds_read_b128 v[158:161], v214 offset:16384
	ds_read_b128 v[164:167], v214 offset:18432
	ds_read_b128 v[168:171], v214 offset:20480
	ds_read_b128 v[172:175], v214 offset:22528
	ds_read_b128 v[176:179], v216 offset:49152
	ds_read_b128 v[180:183], v216 offset:51200
	ds_read_b128 v[192:195], v216 offset:53248
	ds_read_b128 v[210:213], v216 offset:55296
	s_waitcnt lgkmcnt(8)
	v_mfma_f32_16x16x32_bf16 v[62:65], v[142:145], v[126:129], v[62:65]
	v_mfma_f32_16x16x32_bf16 v[66:69], v[146:149], v[126:129], v[66:69]
	v_mfma_f32_16x16x32_bf16 v[70:73], v[150:153], v[126:129], v[70:73]
	v_mfma_f32_16x16x32_bf16 v[2:5], v[154:157], v[126:129], v[2:5]
	v_mfma_f32_16x16x32_bf16 v[14:17], v[142:145], v[130:133], v[14:17]
	v_mfma_f32_16x16x32_bf16 v[22:25], v[146:149], v[130:133], v[22:25]
	v_mfma_f32_16x16x32_bf16 v[30:33], v[150:153], v[130:133], v[30:33]
	v_mfma_f32_16x16x32_bf16 v[18:21], v[154:157], v[130:133], v[18:21]
	v_mfma_f32_16x16x32_bf16 v[26:29], v[142:145], v[134:137], v[26:29]
	v_mfma_f32_16x16x32_bf16 v[34:37], v[146:149], v[134:137], v[34:37]
	v_mfma_f32_16x16x32_bf16 v[58:61], v[150:153], v[134:137], v[58:61]
	v_mfma_f32_16x16x32_bf16 v[38:41], v[154:157], v[134:137], v[38:41]
	v_mfma_f32_16x16x32_bf16 v[46:49], v[142:145], v[138:141], v[46:49]
	v_mfma_f32_16x16x32_bf16 v[50:53], v[146:149], v[138:141], v[50:53]
	v_mfma_f32_16x16x32_bf16 v[54:57], v[150:153], v[138:141], v[54:57]
	v_mfma_f32_16x16x32_bf16 v[10:13], v[154:157], v[138:141], v[10:13]
	s_waitcnt lgkmcnt(0)
	s_barrier
; template <class Epi>
; DEV void gemm_tile(const bf16_t* __restrict__ A, int lda, const bf16_t* __restrict__ Bt, int ldb, int K, int tm, int tn, char* smem, const Epi& epi) {
;     ...
;     float* Ct = (float*)smem;
; #pragma unroll
;     for (int m = 0; m < 4; ++m)
; #pragma unroll
;         for (int n = 0; n < 4; ++n) *(f32x4*)(Ct + (wr * 64 + m * 16 + fr) * CP + wc * 64 + n * 16 + fq * 4) = acc[m][n];
;     __syncthreads();
	v_mfma_f32_16x16x32_bf16 v[62:65], v[176:179], v[158:161], v[62:65]
	v_mfma_f32_16x16x32_bf16 v[66:69], v[180:183], v[158:161], v[66:69]
	v_mfma_f32_16x16x32_bf16 v[70:73], v[192:195], v[158:161], v[70:73]
	v_mfma_f32_16x16x32_bf16 v[2:5], v[210:213], v[158:161], v[2:5]
	v_mfma_f32_16x16x32_bf16 v[14:17], v[176:179], v[164:167], v[14:17]
	v_mfma_f32_16x16x32_bf16 v[22:25], v[180:183], v[164:167], v[22:25]
	v_mfma_f32_16x16x32_bf16 v[30:33], v[192:195], v[164:167], v[30:33]
	v_mfma_f32_16x16x32_bf16 v[18:21], v[210:213], v[164:167], v[18:21]
	v_mfma_f32_16x16x32_bf16 v[26:29], v[176:179], v[168:171], v[26:29]
	v_mfma_f32_16x16x32_bf16 v[34:37], v[180:183], v[168:171], v[34:37]
	v_mfma_f32_16x16x32_bf16 v[58:61], v[192:195], v[168:171], v[58:61]
	v_mfma_f32_16x16x32_bf16 v[38:41], v[210:213], v[168:171], v[38:41]
	v_mfma_f32_16x16x32_bf16 v[46:49], v[176:179], v[172:175], v[46:49]
	v_mfma_f32_16x16x32_bf16 v[50:53], v[180:183], v[172:175], v[50:53]
	v_mfma_f32_16x16x32_bf16 v[54:57], v[192:195], v[172:175], v[54:57]
	v_mfma_f32_16x16x32_bf16 v[10:13], v[210:213], v[172:175], v[10:13]
	s_setprio 0
	v_readlane_b32 s88, v255, 24
	v_readlane_b32 s89, v255, 25
	v_readlane_b32 s90, v255, 26
	v_readlane_b32 s91, v255, 27
	v_readlane_b32 s92, v255, 28
	v_readlane_b32 s93, v255, 29
	v_readlane_b32 s94, v255, 30
	v_readlane_b32 s95, v255, 31
	s_nop 7
	s_nop 1
	s_mul_hi_u32 s39, s39, 0x38e38e39
	s_lshr_b32 s46, s39, 2
	s_mul_i32 s39, s46, 0xfffff700
	s_add_i32 s47, s39, s38
	s_cmpk_lt_i32 s47, 0x800
	s_cselect_b64 s[38:39], -1, 0
	s_mul_i32 s43, s46, 0x6000
	s_and_b64 s[44:45], s[38:39], exec
	v_lshl_or_b32 v7, v8, 6, v7
	s_cselect_b32 s43, s43, 0xc0000
	v_lshl_add_u32 v6, v6, 8, 16
	v_lshlrev_b32_e32 v0, 4, v0
	v_mul_lo_u32 v7, v7, s58
	s_add_u32 s43, s10, s43
	v_add3_u32 v0, v6, v0, v7
	v_mov_b32_e32 v8, v163
	s_addc_u32 s44, s11, 0
	s_lshl_b32 s45, s42, 2
	s_waitcnt vmcnt(0)
	s_barrier
	ds_write_b128 v0, v[62:65]
	ds_write_b128 v0, v[66:69] offset:64
	ds_write_b128 v0, v[70:73] offset:128
	ds_write_b128 v0, v[2:5] offset:192
	ds_write_b128 v0, v[14:17] offset:8448
	ds_write_b128 v0, v[22:25] offset:8512
	ds_write_b128 v0, v[30:33] offset:8576
	ds_write_b128 v0, v[18:21] offset:8640
	ds_write_b128 v0, v[26:29] offset:16896
	ds_write_b128 v0, v[34:37] offset:16960
	ds_write_b128 v0, v[58:61] offset:17024
	ds_write_b128 v0, v[38:41] offset:17088
	ds_write_b128 v0, v[46:49] offset:25344
	ds_write_b128 v0, v[50:53] offset:25408
	ds_write_b128 v0, v[54:57] offset:25472
	ds_write_b128 v0, v[10:13] offset:25536
	s_waitcnt lgkmcnt(0)
	s_barrier
; DEV int tid_() { int t = __builtin_amdgcn_workitem_id_x(); asm volatile("" : "+v"(t)); return t; }
;     DEV void operator()(int tm, int tn, const float* Ct) const {
;         const int row0 = tm * 128, b = row0 / TT, tt0 = row0 - b * TT;
;         const int tid = tid_(), c = (tid & 31) << 2, rb = tid >> 5;
;         const f32x4 g = *(const f32x4*)(mod + (size_t)(tt0 < SEQ ? b : 32) * 6144 + goff + tn * 128 + c);
;         float* x0 = xrow(*p, row0) + tn * 128 + c;
;         const float* xs = from_in ? xrow_in(*p, row0) + tn * 128 + c : x0;
; #pragma unroll
;         for (int it0 = 0; it0 < 16; it0 += 8) {
;             f32x4 xv[8];
; #pragma unroll
;             for (int u = 0; u < 8; ++u) xv[u] = *(const f32x4*)(xs + (size_t)(rb + 8 * (it0 + u)) * D);
; #pragma unroll
;             for (int u = 0; u < 8; ++u) { const int r = rb + 8 * (it0 + u); *(f32x4*)(x0 + (size_t)r * D) = xv[u] + g * *(const f32x4*)(Ct + r * CP + c); }
;         }
	s_add_u32 s42, s43, s45
	v_lshlrev_b32_e32 v0, 4, v8
	s_addc_u32 s43, s44, 0
	v_and_b32_e32 v0, 0x1f0, v0
	v_lshl_add_u64 v[2:3], s[42:43], 0, v[0:1]
	s_movk_i32 s42, 0x5000
	v_add_co_u32_e32 v2, vcc, s42, v2
	s_add_i32 s42, s47, 0xfffff800
	s_ashr_i32 s43, s47, 31
	s_and_b64 s[38:39], s[38:39], exec
	v_readlane_b32 s48, v251, 1
	v_readlane_b32 s51, v251, 4
	v_readlane_b32 s38, v251, 36
	s_cselect_b32 s44, 23, 20
	v_readlane_b32 s49, v251, 2
	v_readlane_b32 s50, v251, 3
	s_cselect_b32 s48, s51, s38
	v_readlane_b32 s38, v251, 35
	s_cselect_b32 s49, s50, s38
	s_cselect_b32 s39, s43, 0
	s_cselect_b32 s38, s47, s42
	s_lshl_b32 s42, s46, s44
	s_add_u32 s42, s49, s42
	s_addc_u32 s43, s48, 0
	s_lshl_b64 s[38:39], s[38:39], 12
	s_add_u32 s38, s42, s38
	s_addc_u32 s39, s43, s39
	s_add_u32 s38, s38, s45
	v_ashrrev_i32_e32 v40, 5, v8
	s_addc_u32 s39, s39, 0
	v_ashrrev_i32_e32 v41, 31, v40
	v_lshl_add_u64 v[6:7], s[38:39], 0, v[0:1]
	v_lshlrev_b64 v[8:9], 12, v[40:41]
	v_addc_co_u32_e32 v3, vcc, 0, v3, vcc
	v_lshl_add_u64 v[6:7], v[6:7], 0, v[8:9]
	global_load_dwordx4 v[2:5], v[2:3], off
	s_mov_b32 s38, 0x8000
	global_load_dwordx4 v[8:11], v[6:7], off
	v_add_co_u32_e32 v44, vcc, s38, v6
	s_mov_b32 s38, 0x10000
	s_nop 0
	v_addc_co_u32_e32 v45, vcc, 0, v7, vcc
	global_load_dwordx4 v[12:15], v[44:45], off
	v_add_co_u32_e32 v46, vcc, s38, v6
	s_mov_b32 s38, 0x18000
	s_nop 0
	v_addc_co_u32_e32 v47, vcc, 0, v7, vcc
	global_load_dwordx4 v[16:19], v[46:47], off
	v_add_co_u32_e32 v48, vcc, s38, v6
	s_mov_b32 s38, 0x20000
	s_nop 0
	v_addc_co_u32_e32 v49, vcc, 0, v7, vcc
	global_load_dwordx4 v[20:23], v[48:49], off
	v_add_co_u32_e32 v50, vcc, s38, v6
	s_mov_b32 s38, 0x28000
	s_nop 0
	v_addc_co_u32_e32 v51, vcc, 0, v7, vcc
	global_load_dwordx4 v[24:27], v[50:51], off
	v_add_co_u32_e32 v52, vcc, s38, v6
	s_mov_b32 s38, 0x30000
	s_nop 0
	v_addc_co_u32_e32 v53, vcc, 0, v7, vcc
	global_load_dwordx4 v[28:31], v[52:53], off
	v_add_co_u32_e32 v54, vcc, s38, v6
	s_mov_b32 s38, 0x38000
	s_nop 0
	v_addc_co_u32_e32 v55, vcc, 0, v7, vcc
	global_load_dwordx4 v[32:35], v[54:55], off
	v_add_co_u32_e32 v56, vcc, s38, v6
	v_mul_lo_u32 v40, v40, s58
	s_nop 0
	v_addc_co_u32_e32 v57, vcc, 0, v7, vcc
	global_load_dwordx4 v[36:39], v[56:57], off
	v_add3_u32 v0, 16, v0, v40
	ds_read_b128 v[40:43], v0
	s_mov_b32 s38, 0x40000
	s_waitcnt vmcnt(7) lgkmcnt(0)
	v_pk_fma_f32 v[10:11], v[4:5], v[42:43], v[10:11]
	v_pk_fma_f32 v[8:9], v[2:3], v[40:41], v[8:9]
	global_store_dwordx4 v[6:7], v[8:11], off
	ds_read_b128 v[8:11], v0 offset:4224
	s_waitcnt vmcnt(7) lgkmcnt(0)
	v_pk_fma_f32 v[10:11], v[4:5], v[10:11], v[14:15]
	v_pk_fma_f32 v[8:9], v[2:3], v[8:9], v[12:13]
	global_store_dwordx4 v[44:45], v[8:11], off
	ds_read_b128 v[8:11], v0 offset:8448
	s_waitcnt vmcnt(7) lgkmcnt(0)
	v_pk_fma_f32 v[10:11], v[4:5], v[10:11], v[18:19]
	v_pk_fma_f32 v[8:9], v[2:3], v[8:9], v[16:17]
	global_store_dwordx4 v[46:47], v[8:11], off
	ds_read_b128 v[8:11], v0 offset:12672
	s_waitcnt vmcnt(7) lgkmcnt(0)
	v_pk_fma_f32 v[10:11], v[4:5], v[10:11], v[22:23]
	v_pk_fma_f32 v[8:9], v[2:3], v[8:9], v[20:21]
	global_store_dwordx4 v[48:49], v[8:11], off
	ds_read_b128 v[8:11], v0 offset:16896
	s_waitcnt vmcnt(7) lgkmcnt(0)
	v_pk_fma_f32 v[10:11], v[4:5], v[10:11], v[26:27]
	v_pk_fma_f32 v[8:9], v[2:3], v[8:9], v[24:25]
	global_store_dwordx4 v[50:51], v[8:11], off
	ds_read_b128 v[8:11], v0 offset:21120
	ds_read_b128 v[48:51], v0 offset:33792
	s_waitcnt vmcnt(7) lgkmcnt(1)
	v_pk_fma_f32 v[10:11], v[4:5], v[10:11], v[30:31]
	v_pk_fma_f32 v[8:9], v[2:3], v[8:9], v[28:29]
	global_store_dwordx4 v[52:53], v[8:11], off
	ds_read_b128 v[8:11], v0 offset:25344
	v_add_co_u32_e32 v52, vcc, s38, v6
	s_mov_b32 s38, 0x48000
	s_nop 0
	v_addc_co_u32_e32 v53, vcc, 0, v7, vcc
	s_waitcnt vmcnt(7) lgkmcnt(0)
	v_pk_fma_f32 v[10:11], v[4:5], v[10:11], v[34:35]
	v_pk_fma_f32 v[8:9], v[2:3], v[8:9], v[32:33]
	global_store_dwordx4 v[54:55], v[8:11], off
	ds_read_b128 v[8:11], v0 offset:29568
	v_add_co_u32_e32 v54, vcc, s38, v6
	s_mov_b32 s38, 0x50000
	s_nop 0
	v_addc_co_u32_e32 v55, vcc, 0, v7, vcc
	s_waitcnt vmcnt(7) lgkmcnt(0)
	v_pk_fma_f32 v[10:11], v[4:5], v[10:11], v[38:39]
	v_pk_fma_f32 v[8:9], v[2:3], v[8:9], v[36:37]
	global_load_dwordx4 v[36:39], v[52:53], off
	global_load_dwordx4 v[40:43], v[54:55], off
	s_nop 0
	global_store_dwordx4 v[56:57], v[8:11], off
	v_add_co_u32_e32 v56, vcc, s38, v6
	s_mov_b32 s38, 0x58000
	s_nop 0
	v_addc_co_u32_e32 v57, vcc, 0, v7, vcc
	global_load_dwordx4 v[44:47], v[56:57], off
	v_add_co_u32_e32 v34, vcc, s38, v6
	s_mov_b32 s38, 0x60000
	s_nop 0
	v_addc_co_u32_e32 v35, vcc, 0, v7, vcc
	global_load_dwordx4 v[22:25], v[34:35], off
	v_add_co_u32_e32 v32, vcc, s38, v6
	s_mov_b32 s38, 0x68000
	s_nop 0
	v_addc_co_u32_e32 v33, vcc, 0, v7, vcc
	global_load_dwordx4 v[18:21], v[32:33], off
	v_add_co_u32_e32 v30, vcc, s38, v6
	s_mov_b32 s38, 0x70000
	s_nop 0
	v_addc_co_u32_e32 v31, vcc, 0, v7, vcc
	global_load_dwordx4 v[14:17], v[30:31], off
	v_add_co_u32_e32 v28, vcc, s38, v6
	s_mov_b32 s38, 0x78000
	s_nop 0
	v_addc_co_u32_e32 v29, vcc, 0, v7, vcc
	global_load_dwordx4 v[10:13], v[28:29], off
	v_add_co_u32_e32 v26, vcc, s38, v6
	s_waitcnt vmcnt(7)
	v_pk_fma_f32 v[38:39], v[4:5], v[50:51], v[38:39]
	v_addc_co_u32_e32 v27, vcc, 0, v7, vcc
	global_load_dwordx4 v[6:9], v[26:27], off
	v_pk_fma_f32 v[36:37], v[2:3], v[48:49], v[36:37]
	global_store_dwordx4 v[52:53], v[36:39], off
	ds_read_b128 v[36:39], v0 offset:38016
	s_waitcnt vmcnt(8) lgkmcnt(0)
	v_pk_fma_f32 v[38:39], v[4:5], v[38:39], v[42:43]
	v_pk_fma_f32 v[36:37], v[2:3], v[36:37], v[40:41]
	global_store_dwordx4 v[54:55], v[36:39], off
	ds_read_b128 v[36:39], v0 offset:42240
	s_waitcnt vmcnt(7) lgkmcnt(0)
	v_pk_fma_f32 v[38:39], v[4:5], v[38:39], v[46:47]
	v_pk_fma_f32 v[36:37], v[2:3], v[36:37], v[44:45]
	global_store_dwordx4 v[56:57], v[36:39], off
	ds_read_b128 v[36:39], v0 offset:46464
	s_waitcnt vmcnt(7) lgkmcnt(0)
	v_pk_fma_f32 v[24:25], v[4:5], v[38:39], v[24:25]
	v_pk_fma_f32 v[22:23], v[2:3], v[36:37], v[22:23]
	global_store_dwordx4 v[34:35], v[22:25], off
	ds_read_b128 v[22:25], v0 offset:50688
	s_waitcnt vmcnt(7) lgkmcnt(0)
	v_pk_fma_f32 v[20:21], v[4:5], v[24:25], v[20:21]
	v_pk_fma_f32 v[18:19], v[2:3], v[22:23], v[18:19]
	global_store_dwordx4 v[32:33], v[18:21], off
	ds_read_b128 v[18:21], v0 offset:54912
	s_waitcnt vmcnt(7) lgkmcnt(0)
	v_pk_fma_f32 v[16:17], v[4:5], v[20:21], v[16:17]
	v_pk_fma_f32 v[14:15], v[2:3], v[18:19], v[14:15]
	global_store_dwordx4 v[30:31], v[14:17], off
	ds_read_b128 v[14:17], v0 offset:59136
	s_waitcnt vmcnt(7) lgkmcnt(0)
	v_pk_fma_f32 v[12:13], v[4:5], v[16:17], v[12:13]
	v_pk_fma_f32 v[10:11], v[2:3], v[14:15], v[10:11]
	global_store_dwordx4 v[28:29], v[10:13], off
	ds_read_b128 v[10:13], v0 offset:63360
	s_waitcnt vmcnt(7) lgkmcnt(0)
	v_pk_fma_f32 v[4:5], v[4:5], v[12:13], v[8:9]
	v_pk_fma_f32 v[2:3], v[2:3], v[10:11], v[6:7]
	global_store_dwordx4 v[26:27], v[2:5], off
	s_barrier
	s_branch .LBB0_178

; DEV int tid_() { int t = __builtin_amdgcn_workitem_id_x(); asm volatile("" : "+v"(t)); return t; }
; template <class Epi>
; DEV void gemm_tile(const bf16_t* __restrict__ A, int lda, const bf16_t* __restrict__ Bt, int ldb, int K, int tm, int tn, char* smem, const Epi& epi) {
;     const int tid = tid_(), lane = tid & 63, wid = tid >> 6, wr = wid >> 1, wc = wid & 1, fr = lane & 15, fq = lane >> 4;
;     bf16_t* As = (bf16_t*)smem;
;     bf16_t* Bs = As + 2 * 128 * 64;
;     const int lrow = tid >> 3, lcc = (tid & 7) * 8, lsw = (((tid & 7) ^ (lrow & 7)) * 8);
;     const bf16_t* Ag = A + (size_t)(tm * 128 + lrow) * lda + lcc;
;     const bf16_t* Bg = Bt + (size_t)(tn * 128 + lrow) * ldb + lcc;
;     f32x4 acc[4][4];
; #pragma unroll
;     for (int m = 0; m < 4; ++m)
; #pragma unroll
;         for (int n = 0; n < 4; ++n) acc[m][n] = (f32x4){0.f, 0.f, 0.f, 0.f};
;     const int gsw = (((tid & 7) ^ (lrow & 7)) * 8);
;     const bf16_t* Ad = A + (size_t)(tm * 128 + lrow) * lda + gsw;
;     const bf16_t* Bd = Bt + (size_t)(tn * 128 + lrow) * ldb + gsw;
;     char* Asb = (char*)As; char* Bsb = (char*)Bs;
;     ...
;     const int nk = K >> 6;
;     G_DMA(0, 0);
;     asm volatile("s_waitcnt vmcnt(0)" ::: "memory");
;     __syncthreads();
; #pragma unroll 4
;     for (int kt = 0; kt < nk; ++kt) {
;         const int cur = kt & 1;
;         if (kt + 1 < nk) G_DMA(cur ^ 1, kt + 1);
.LBB0_683:
	v_readlane_b32 s0, v253, 32
	s_add_i32 s48, s2, s0
	v_mov_b32_e32 v12, v163
	s_lshl_b32 s51, s48, 7
	v_ashrrev_i32_e32 v14, 3, v12
	s_lshl_b32 s50, s62, 7
	v_add_u32_e32 v2, s51, v14
	v_add_u32_e32 v4, s50, v14
	v_ashrrev_i32_e32 v3, 31, v2
	v_ashrrev_i32_e32 v5, 31, v4
	s_waitcnt vmcnt(10)
	v_xor_b32_e32 v0, v14, v12
	v_lshlrev_b64 v[2:3], 11, v[2:3]
	v_lshlrev_b64 v[4:5], 11, v[4:5]
	v_lshlrev_b32_e32 v0, 4, v0
	v_lshl_add_u64 v[6:7], s[38:39], 0, v[2:3]
	v_lshl_add_u64 v[8:9], s[40:41], 0, v[4:5]
	v_and_b32_e32 v0, 0x70, v0
	v_lshl_add_u64 v[6:7], v[6:7], 0, v[0:1]
	v_lshl_add_u64 v[8:9], v[8:9], 0, v[0:1]
	v_lshlrev_b32_e32 v0, 4, v12
	v_add_u32_e32 v0, 16, v0
	v_add_u32_e32 v76, 0x8000, v0
	v_readfirstlane_b32 s0, v0
	s_mov_b32 m0, s0
	v_readfirstlane_b32 s0, v76
	v_add_u32_e32 v77, 0x1000, v0
	global_load_lds_dwordx4 v[6:7], off
	s_mov_b32 m0, s0
	s_mov_b64 s[2:3], 0x10000
	v_readfirstlane_b32 s0, v77
	v_add_u32_e32 v78, 0x9000, v0
	global_load_lds_dwordx4 v[8:9], off
	v_lshl_add_u64 v[10:11], v[6:7], 0, s[2:3]
	s_mov_b32 m0, s0
	v_readfirstlane_b32 s0, v78
	v_add_u32_e32 v79, 0x2000, v0
	global_load_lds_dwordx4 v[10:11], off
	v_lshl_add_u64 v[10:11], v[8:9], 0, s[2:3]
	s_mov_b32 m0, s0
	s_mov_b64 s[2:3], 0x20000
	v_readfirstlane_b32 s0, v79
	v_add_u32_e32 v80, 0xa000, v0
	global_load_lds_dwordx4 v[10:11], off
	v_lshl_add_u64 v[10:11], v[6:7], 0, s[2:3]
	s_mov_b32 m0, s0
	v_readfirstlane_b32 s0, v80
	v_add_u32_e32 v81, 0x3000, v0
	global_load_lds_dwordx4 v[10:11], off
	v_lshl_add_u64 v[10:11], v[8:9], 0, s[2:3]
	s_mov_b32 m0, s0
	s_mov_b64 s[2:3], 0x30000
	v_readfirstlane_b32 s0, v81
	v_add_u32_e32 v82, 0xb000, v0
	global_load_lds_dwordx4 v[10:11], off
	v_lshl_add_u64 v[6:7], v[6:7], 0, s[2:3]
	s_mov_b32 m0, s0
	v_readfirstlane_b32 s0, v82
	global_load_lds_dwordx4 v[6:7], off
	v_lshl_add_u64 v[6:7], v[8:9], 0, s[2:3]
	s_mov_b32 m0, s0
	v_lshrrev_b32_e32 v13, 4, v12
	global_load_lds_dwordx4 v[6:7], off
	v_and_b32_e32 v75, 15, v12
	v_ashrrev_i32_e32 v84, 7, v12
	v_bfe_u32 v83, v12, 4, 2
	v_and_b32_e32 v8, 7, v12
	v_lshlrev_b32_e32 v6, 13, v84
	v_lshlrev_b32_e32 v7, 7, v75
	v_bitop3_b32 v9, v13, v8, 3 bitop3:0x6c
	v_bitop3_b32 v8, v83, v8, 4 bitop3:0x36
	v_add3_u32 v6, 16, v6, v7
	v_lshlrev_b32_e32 v9, 4, v9
	v_lshlrev_b32_e32 v8, 4, v8
	v_add_u32_e32 v85, v6, v9
	v_add_u32_e32 v87, v6, v8
	v_bitop3_b32 v6, v14, 7, v12 bitop3:0x48
	v_bfe_u32 v74, v12, 6, 1
	v_lshlrev_b32_e32 v6, 4, v6
	s_waitcnt vmcnt(0)
	v_lshlrev_b32_e32 v10, 13, v74
	v_or_b32_e32 v2, v2, v6
	v_add3_u32 v7, 16, v10, v7
	v_or_b32_e32 v4, v4, v6
	v_lshl_add_u64 v[68:69], s[44:45], 0, v[2:3]
	v_mov_b32_e32 v2, 0
	v_add_u32_e32 v86, v7, v9
	v_add_u32_e32 v88, v7, v8
	v_lshl_add_u64 v[66:67], s[42:43], 0, v[4:5]
	s_mov_b64 s[0:1], 0
	v_mov_b32_e32 v3, v2
	v_mov_b32_e32 v4, v2
	v_mov_b32_e32 v5, v2
	v_mov_b32_e32 v6, v2
	v_mov_b32_e32 v7, v2
	v_mov_b32_e32 v8, v2
	v_mov_b32_e32 v9, v2
	v_mov_b32_e32 v10, v2
	v_mov_b32_e32 v11, v2
	v_mov_b32_e32 v12, v2
	v_mov_b32_e32 v13, v2
	v_mov_b32_e32 v14, v2
	v_mov_b32_e32 v15, v2
	v_mov_b32_e32 v16, v2
	v_mov_b32_e32 v17, v2
	s_waitcnt vmcnt(0)
	v_mov_b32_e32 v18, v2
	v_mov_b32_e32 v19, v2
	v_mov_b32_e32 v20, v2
	v_mov_b32_e32 v21, v2
	v_mov_b32_e32 v22, v2
	v_mov_b32_e32 v23, v2
	v_mov_b32_e32 v24, v2
	v_mov_b32_e32 v25, v2
	s_waitcnt vmcnt(0)
	v_mov_b32_e32 v26, v2
	v_mov_b32_e32 v27, v2
	v_mov_b32_e32 v28, v2
	v_mov_b32_e32 v29, v2
	v_mov_b32_e32 v30, v2
	v_mov_b32_e32 v31, v2
	v_mov_b32_e32 v32, v2
	v_mov_b32_e32 v33, v2
	v_mov_b32_e32 v34, v2
	v_mov_b32_e32 v35, v2
	v_mov_b32_e32 v36, v2
	v_mov_b32_e32 v37, v2
	v_mov_b32_e32 v38, v2
	v_mov_b32_e32 v39, v2
	v_mov_b32_e32 v40, v2
	v_mov_b32_e32 v41, v2
	v_mov_b32_e32 v42, v2
	v_mov_b32_e32 v43, v2
	v_mov_b32_e32 v44, v2
	v_mov_b32_e32 v45, v2
	v_mov_b32_e32 v46, v2
	v_mov_b32_e32 v47, v2
	v_mov_b32_e32 v48, v2
	v_mov_b32_e32 v49, v2
	v_mov_b32_e32 v50, v2
	v_mov_b32_e32 v51, v2
	v_mov_b32_e32 v52, v2
	v_mov_b32_e32 v53, v2
	v_mov_b32_e32 v54, v2
	v_mov_b32_e32 v55, v2
	v_mov_b32_e32 v56, v2
	v_mov_b32_e32 v57, v2
	v_mov_b32_e32 v58, v2
	v_mov_b32_e32 v59, v2
	v_mov_b32_e32 v60, v2
	v_mov_b32_e32 v61, v2
	v_mov_b32_e32 v62, v2
	v_mov_b32_e32 v63, v2
	v_mov_b32_e32 v64, v2
	v_mov_b32_e32 v65, v2
	s_waitcnt lgkmcnt(0)
	s_barrier
	v_writelane_b32 v255, s88, 24
	v_writelane_b32 v255, s89, 25
	v_writelane_b32 v255, s90, 26
	v_writelane_b32 v255, s91, 27
	v_writelane_b32 v255, s92, 28
	v_writelane_b32 v255, s93, 29
	v_writelane_b32 v255, s94, 30
	v_writelane_b32 v255, s95, 31
	v_readfirstlane_b32 s88, v68
	v_readfirstlane_b32 s89, v69
	v_readfirstlane_b32 s90, v66
	v_readfirstlane_b32 s91, v67
	v_lshl_add_u32 v242, v163, 4, 16
	s_and_b32 s88, s88, 0xffffff80
	s_and_b32 s90, s90, 0xffffff80
	v_readfirstlane_b32 s93, v242
	v_subrev_u32_e32 v250, s88, v68
	v_subrev_u32_e32 v246, s90, v66
	v_add_u32_e32 v249, 0x10000, v250
	v_add_u32_e32 v245, 0x10000, v246
	v_add_u32_e32 v248, 0x20000, v250
	v_add_u32_e32 v244, 0x20000, v246
	v_add_u32_e32 v247, 0x30000, v250
	v_add_u32_e32 v243, 0x30000, v246
	s_add_u32 s94, s93, 0x4000
	s_add_u32 s88, s88, 0x8688080
	s_addc_u32 s89, s89, 0
	s_add_u32 s90, s90, 0x23a8080
	s_addc_u32 s91, s91, 0
	v_and_b32_e32 v242, 15, v163
	v_lshlrev_b32_e32 v242, 7, v242
	v_bfe_u32 v153, v163, 4, 2
	v_and_b32_e32 v154, 7, v163
	v_xor_b32_e32 v153, v153, v154
	v_lshlrev_b32_e32 v154, 4, v153
	v_xor_b32_e32 v153, 4, v153
	v_lshlrev_b32_e32 v153, 4, v153
	v_lshrrev_b32_e32 v89, 7, v163
	v_lshl_add_u32 v89, v89, 13, v242
	v_add_u32_e32 v89, 16, v89
	v_bfe_u32 v151, v163, 6, 1
	v_lshl_add_u32 v151, v151, 13, v242
	v_add_u32_e32 v151, 16, v151
	v_add_u32_e32 v150, v89, v153
	v_add_u32_e32 v152, v151, v153
	v_add_u32_e32 v89, v89, v154
	v_add_u32_e32 v151, v151, v154
	s_mov_b32 m0, s94
	s_nop 0
	global_load_lds_dwordx4 v250, s[88:89]
	s_add_u32 m0, m0, 0x1000
	s_nop 0
	global_load_lds_dwordx4 v249, s[88:89]
	s_add_u32 m0, m0, 0x1000
	s_nop 0
	global_load_lds_dwordx4 v248, s[88:89]
	s_add_u32 m0, m0, 0x1000
	s_nop 0
	global_load_lds_dwordx4 v247, s[88:89]
	s_add_u32 m0, m0, 0x5000
	s_nop 0
	global_load_lds_dwordx4 v246, s[90:91]
	s_add_u32 m0, m0, 0x1000
	s_nop 0
	global_load_lds_dwordx4 v245, s[90:91]
	s_add_u32 m0, m0, 0x1000
	s_nop 0
	global_load_lds_dwordx4 v244, s[90:91]
	s_add_u32 m0, m0, 0x1000
	s_nop 0
	global_load_lds_dwordx4 v243, s[90:91]
	s_add_u32 s88, s88, 0x80
	s_addc_u32 s89, s89, 0
	s_add_u32 s90, s90, 0x80
	s_addc_u32 s91, s91, 0
	ds_read_b128 v[70:73], v89
	ds_read_b128 v[90:93], v89 offset:2048
	ds_read_b128 v[94:97], v89 offset:4096
	ds_read_b128 v[98:101], v89 offset:6144
	ds_read_b128 v[102:105], v151 offset:32768
	ds_read_b128 v[106:109], v151 offset:34816
	ds_read_b128 v[110:113], v151 offset:36864
	ds_read_b128 v[114:117], v151 offset:38912
	v_readlane_b32 s95, v251, 0
	s_nop 0
	s_cmp_lt_u32 s95, 0x100
	s_setprio 1
	s_cbranch_scc1 .Lgemm_in_lowprio
	s_setprio 2
